# split packed f32 VALU ops into scalar pairs in attention phases and rope epilogue
# baseline (speedup 1.0000x reference)
.LBB0_122:
	s_or_b64 exec, exec, s[38:39]
	v_lshlrev_b64 v[2:3], 2, v[136:137]
	v_lshl_add_u64 v[4:5], s[16:17], 0, v[2:3]
	v_lshl_add_u64 v[4:5], v[4:5], 0, v[0:1]
	v_lshl_add_u64 v[2:3], s[18:19], 0, v[2:3]
	v_lshl_add_u64 v[2:3], v[2:3], 0, v[0:1]
	global_load_dwordx4 v[120:123], v[4:5], off offset:16
	global_load_dwordx4 v[124:127], v[4:5], off
	global_load_dwordx4 v[112:115], v[2:3], off offset:16
	global_load_dwordx4 v[116:119], v[2:3], off
	s_and_b64 vcc, exec, s[24:25]
	v_mul_f32_e32 v165, 0x3fb8aa3b, v6
	s_cbranch_vccnz .LBB0_128
	ds_read_b128 v[2:5], v139
	ds_read_b128 v[18:21], v139 offset:32
	ds_read_b128 v[22:25], v139 offset:64
	ds_read_b128 v[26:29], v139 offset:96
	s_mov_b32 s0, 0xff800000
	s_waitcnt lgkmcnt(3)
	v_mfma_f32_32x32x16_bf16 v[2:17], v[2:5], v[96:99], 0
	s_waitcnt lgkmcnt(2)
	v_mfma_f32_32x32x16_bf16 v[2:17], v[18:21], v[100:103], v[2:17]
	s_waitcnt lgkmcnt(1)
	v_mfma_f32_32x32x16_bf16 v[2:17], v[22:25], v[104:107], v[2:17]
	s_waitcnt lgkmcnt(0)
	v_mfma_f32_32x32x16_bf16 v[2:17], v[26:29], v[108:111], v[2:17]
	s_nop 11
	v_mul_f32_e32 v18, 0x3fb8aa3b, v3
	v_mul_f32_e32 v0, 0x3fb8aa3b, v2
	v_mul_f32_e32 v19, 0x3fb8aa3b, v4
	v_mul_f32_e32 v20, 0x3fb8aa3b, v5
	v_max_f32_e32 v18, 0xff800000, v18
	v_mul_f32_e32 v21, 0x3fb8aa3b, v6
	v_mul_f32_e32 v22, 0x3fb8aa3b, v7
	v_max3_f32 v0, v0, s0, v18
	v_max_f32_e32 v18, 0xff800000, v19
	v_max_f32_e32 v19, 0xff800000, v20
	v_mul_f32_e32 v23, 0x3fb8aa3b, v8
	v_mul_f32_e32 v24, 0x3fb8aa3b, v9
	v_max3_f32 v0, v0, v18, v19
	v_max_f32_e32 v18, 0xff800000, v21
	v_max_f32_e32 v19, 0xff800000, v22
	v_mul_f32_e32 v25, 0x3fb8aa3b, v10
	v_mul_f32_e32 v26, 0x3fb8aa3b, v11
	v_max3_f32 v0, v0, v18, v19
	v_max_f32_e32 v18, 0xff800000, v23
	v_max_f32_e32 v19, 0xff800000, v24
	v_mul_f32_e32 v27, 0x3fb8aa3b, v12
	v_mul_f32_e32 v28, 0x3fb8aa3b, v13
	v_max3_f32 v0, v0, v18, v19
	v_max_f32_e32 v18, 0xff800000, v25
	v_max_f32_e32 v19, 0xff800000, v26
	v_mul_f32_e32 v29, 0x3fb8aa3b, v14
	v_mul_f32_e32 v30, 0x3fb8aa3b, v15
	v_max3_f32 v0, v0, v18, v19
	v_max_f32_e32 v18, 0xff800000, v27
	v_max_f32_e32 v19, 0xff800000, v28
	v_mul_f32_e32 v31, 0x3fb8aa3b, v16
	v_mul_f32_e32 v32, 0x3fb8aa3b, v17
	v_max3_f32 v0, v0, v18, v19
	v_max_f32_e32 v18, 0xff800000, v29
	v_max_f32_e32 v19, 0xff800000, v30
	v_max3_f32 v0, v0, v18, v19
	v_max_f32_e32 v18, 0xff800000, v31
	v_max_f32_e32 v19, 0xff800000, v32
	v_max3_f32 v0, v0, v18, v19
	v_and_b32_e32 v19, 64, v199
	v_xor_b32_e32 v18, 32, v199
	v_add_u32_e32 v19, 64, v19
	v_cmp_lt_i32_e32 vcc, v18, v19
	s_nop 1
	v_cndmask_b32_e32 v18, v199, v18, vcc
	v_lshlrev_b32_e32 v18, 2, v18
	ds_bpermute_b32 v18, v18, v0
	s_waitcnt lgkmcnt(0)
	v_max3_f32 v64, v165, v0, v18
	v_fma_f32 v0, v2, s68, -v64
	v_exp_f32_e32 v65, v0
	v_sub_f32_e32 v0, 0xff800000, v64
	v_exp_f32_e32 v0, v0
	v_fma_f32 v3, v3, s68, -v64
	v_exp_f32_e32 v66, v3
	v_sub_f32_e32 v18, v165, v64
	v_add_f32_e32 v2, v65, v0
	v_add_f32_e32 v2, 0, v2
	v_add_f32_e32 v3, v66, v0
	v_add_f32_e32 v2, v3, v2
	v_fma_f32 v3, v4, s68, -v64
	v_exp_f32_e32 v67, v3
	v_mov_b32_e32 v165, v64
	v_add_f32_e32 v3, v67, v0
	v_add_f32_e32 v2, v3, v2
	v_fma_f32 v3, v5, s68, -v64
	v_exp_f32_e32 v68, v3
	s_nop 0
	v_add_f32_e32 v3, v68, v0
	v_add_f32_e32 v4, v3, v2
	v_fma_f32 v2, v6, s68, -v64
	v_exp_f32_e32 v33, v2
	v_fma_f32 v2, v7, s68, -v64
	v_exp_f32_e32 v32, v2
	s_nop 0
	v_add_f32_e32 v2, v32, v0
	v_add_f32_e32 v3, v33, v0
	s_nop 0
	v_add_f32_e32 v3, v3, v4
	v_add_f32_e32 v4, v2, v3
	v_fma_f32 v2, v8, s68, -v64
	v_exp_f32_e32 v35, v2
	v_fma_f32 v2, v9, s68, -v64
	v_exp_f32_e32 v34, v2
	s_nop 0
	v_add_f32_e32 v2, v34, v0
	v_add_f32_e32 v3, v35, v0
	s_nop 0
	v_add_f32_e32 v3, v3, v4
	v_add_f32_e32 v4, v2, v3
	v_fma_f32 v2, v10, s68, -v64
	v_exp_f32_e32 v57, v2
	v_fma_f32 v2, v11, s68, -v64
	v_exp_f32_e32 v56, v2
	s_nop 0
	v_add_f32_e32 v2, v56, v0
	v_add_f32_e32 v3, v57, v0
	s_nop 0
	v_add_f32_e32 v3, v3, v4
	v_add_f32_e32 v4, v2, v3
	v_fma_f32 v2, v12, s68, -v64
	v_exp_f32_e32 v59, v2
	v_fma_f32 v2, v13, s68, -v64
	v_exp_f32_e32 v58, v2
	s_nop 0
	v_add_f32_e32 v2, v58, v0
	v_add_f32_e32 v3, v59, v0
	s_nop 0
	v_add_f32_e32 v3, v3, v4
	v_add_f32_e32 v4, v2, v3
	v_fma_f32 v2, v14, s68, -v64
	v_exp_f32_e32 v61, v2
	v_fma_f32 v2, v15, s68, -v64
	v_exp_f32_e32 v60, v2
	s_nop 0
	v_add_f32_e32 v2, v60, v0
	v_add_f32_e32 v3, v61, v0
	s_nop 0
	v_add_f32_e32 v3, v3, v4
	v_add_f32_e32 v4, v2, v3
	v_fma_f32 v2, v16, s68, -v64
	v_exp_f32_e32 v63, v2
	v_fma_f32 v2, v17, s68, -v64
	v_exp_f32_e32 v62, v2
	s_nop 0
	v_add_f32_e32 v2, v62, v0
	v_add_f32_e32 v3, v63, v0
	s_nop 0
	v_add_f32_e32 v0, v3, v4
	v_add_f32_e32 v2, v2, v0
	v_exp_f32_e32 v0, v18
	ds_read_b64_tr_b16 v[48:49], v135 offset:0
	ds_read_b64_tr_b16 v[50:51], v135 offset:1536
	ds_read_b64_tr_b16 v[12:13], v135 offset:64
	ds_read_b64_tr_b16 v[14:15], v135 offset:1600
	ds_read_b64_tr_b16 v[8:9], v135 offset:3072
	ds_read_b64_tr_b16 v[10:11], v135 offset:4608
	ds_read_b64_tr_b16 v[4:5], v135 offset:3136
	ds_read_b64_tr_b16 v[6:7], v135 offset:4672
	ds_read_b64_tr_b16 v[36:37], v135 offset:6144
	ds_read_b64_tr_b16 v[38:39], v135 offset:7680
	ds_read_b64_tr_b16 v[40:41], v135 offset:6208
	ds_read_b64_tr_b16 v[42:43], v135 offset:7744
	ds_read_b64_tr_b16 v[44:45], v135 offset:9216
	ds_read_b64_tr_b16 v[46:47], v135 offset:10752
	ds_read_b64_tr_b16 v[52:53], v135 offset:9280
	ds_read_b64_tr_b16 v[54:55], v135 offset:10816
	s_waitcnt lgkmcnt(0)
	s_nop 0
	v_cvt_pk_bf16_f32 v52, v65, v66
	v_cmp_eq_f32_e32 vcc, 1.0, v0
	s_cmp_lg_u64 vcc, exec
	v_fmac_f32_e32 v2, v129, v0
	v_mul_f32_e32 v0, 0, v0
	s_cselect_b64 vcc, -1, 0
	v_cndmask_b32_e32 v16, 0, v0, vcc
	v_mov_b32_e32 v17, v16
	v_mov_b32_e32 v18, v16
	v_mov_b32_e32 v19, v16
	v_mov_b32_e32 v20, v16
	v_mov_b32_e32 v21, v16
	v_mov_b32_e32 v22, v16
	v_mov_b32_e32 v23, v16
	v_mov_b32_e32 v24, v16
	v_mov_b32_e32 v25, v16
	v_mov_b32_e32 v26, v16
	v_mov_b32_e32 v27, v16
	v_mov_b32_e32 v28, v16
	v_mov_b32_e32 v29, v16
	v_mov_b32_e32 v30, v16
	v_mov_b32_e32 v31, v16
	v_cvt_pk_bf16_f32 v53, v67, v68
	v_cvt_pk_bf16_f32 v54, v33, v32
	v_cvt_pk_bf16_f32 v55, v35, v34
	s_nop 1
	v_mfma_f32_32x32x16_bf16 v[32:47], v[48:51], v[52:55], v[16:31]
	v_mfma_f32_32x32x16_bf16 v[16:31], v[12:15], v[52:55], v[16:31]
	v_cvt_pk_bf16_f32 v12, v57, v56
	v_cvt_pk_bf16_f32 v13, v59, v58
	v_cvt_pk_bf16_f32 v14, v61, v60
	v_cvt_pk_bf16_f32 v15, v63, v62
	s_nop 0
	v_mfma_f32_32x32x16_bf16 v[32:47], v[8:11], v[12:15], v[32:47]
	v_mfma_f32_32x32x16_bf16 v[16:31], v[4:7], v[12:15], v[16:31]
	s_and_b64 vcc, exec, s[24:25]
	s_cbranch_vccz .LBB0_129

.LBB0_129:
	ds_read_b128 v[4:7], v139 offset:9216
	s_waitcnt lgkmcnt(0)
	v_mfma_f32_32x32x16_bf16 v[48:63], v[4:7], v[96:99], 0
	ds_read_b128 v[4:7], v139 offset:13824
	s_waitcnt lgkmcnt(0)
	v_mfma_f32_32x32x16_bf16 v[64:79], v[4:7], v[96:99], 0
	ds_read_b128 v[4:7], v139 offset:9248
	s_waitcnt lgkmcnt(0)
	v_mfma_f32_32x32x16_bf16 v[48:63], v[4:7], v[100:103], v[48:63]
	ds_read_b128 v[4:7], v139 offset:13856
	s_waitcnt lgkmcnt(0)
	v_mfma_f32_32x32x16_bf16 v[64:79], v[4:7], v[100:103], v[64:79]
	ds_read_b128 v[4:7], v139 offset:9280
	s_waitcnt lgkmcnt(0)
	v_mfma_f32_32x32x16_bf16 v[48:63], v[4:7], v[104:107], v[48:63]
	ds_read_b128 v[4:7], v139 offset:13888
	s_waitcnt lgkmcnt(0)
	v_mfma_f32_32x32x16_bf16 v[64:79], v[4:7], v[104:107], v[64:79]
	ds_read_b128 v[4:7], v139 offset:9312
	s_waitcnt lgkmcnt(0)
	v_mfma_f32_32x32x16_bf16 v[48:63], v[4:7], v[108:111], v[48:63]
	ds_read_b128 v[4:7], v139 offset:13920
	s_waitcnt lgkmcnt(0)
	v_mfma_f32_32x32x16_bf16 v[64:79], v[4:7], v[108:111], v[64:79]
	s_nop 8
	v_mul_f32_e32 v172, 0x3fb8aa3b, v49
	v_mul_f32_e32 v173, 0x3fb8aa3b, v48
	v_mul_f32_e32 v170, 0x3fb8aa3b, v50
	v_mul_f32_e32 v168, 0x3fb8aa3b, v51
	v_mul_f32_e32 v166, 0x3fb8aa3b, v52
	v_mul_f32_e32 v51, 0x3fb8aa3b, v56
	v_mul_f32_e32 v49, 0x3fb8aa3b, v57
	v_mul_f32_e32 v171, 0x3fb8aa3b, v65
	v_mul_f32_e32 v174, 0x3fb8aa3b, v64
	v_mul_f32_e32 v169, 0x3fb8aa3b, v66
	v_mul_f32_e32 v167, 0x3fb8aa3b, v67
	v_max_f32_e32 v0, v172, v171
	v_mul_f32_e32 v67, 0x3fb8aa3b, v68
	v_mul_f32_e32 v66, 0x3fb8aa3b, v53
	v_mul_f32_e32 v65, 0x3fb8aa3b, v69
	v_mul_f32_e32 v53, 0x3fb8aa3b, v55
	v_max3_f32 v0, v173, v174, v0
	v_max_f32_e32 v3, v170, v169
	v_max_f32_e32 v55, v168, v167
	v_mul_f32_e32 v64, 0x3fb8aa3b, v54
	v_mul_f32_e32 v54, 0x3fb8aa3b, v70
	v_mul_f32_e32 v52, 0x3fb8aa3b, v71
	v_max3_f32 v0, v0, v3, v55
	v_max_f32_e32 v3, v166, v67
	v_max_f32_e32 v55, v66, v65
	v_mul_f32_e32 v50, 0x3fb8aa3b, v72
	v_mul_f32_e32 v48, 0x3fb8aa3b, v73
	v_max3_f32 v0, v0, v3, v55
	v_max_f32_e32 v3, v64, v54
	v_max_f32_e32 v55, v53, v52
	v_mul_f32_e32 v15, 0x3fb8aa3b, v58
	v_mul_f32_e32 v14, 0x3fb8aa3b, v74
	v_mul_f32_e32 v13, 0x3fb8aa3b, v59
	v_mul_f32_e32 v12, 0x3fb8aa3b, v75
	v_max3_f32 v0, v0, v3, v55
	v_max_f32_e32 v3, v51, v50
	v_max_f32_e32 v55, v49, v48
	v_mul_f32_e32 v11, 0x3fb8aa3b, v60
	v_mul_f32_e32 v10, 0x3fb8aa3b, v76
	v_mul_f32_e32 v9, 0x3fb8aa3b, v61
	v_mul_f32_e32 v8, 0x3fb8aa3b, v77
	v_max3_f32 v0, v0, v3, v55
	v_max_f32_e32 v3, v15, v14
	v_max_f32_e32 v55, v13, v12
	v_mul_f32_e32 v7, 0x3fb8aa3b, v62
	v_mul_f32_e32 v6, 0x3fb8aa3b, v78
	v_mul_f32_e32 v5, 0x3fb8aa3b, v63
	v_mul_f32_e32 v4, 0x3fb8aa3b, v79
	v_max3_f32 v0, v0, v3, v55
	v_max_f32_e32 v3, v11, v10
	v_max_f32_e32 v55, v9, v8
	v_max3_f32 v0, v0, v3, v55
	v_max_f32_e32 v3, v7, v6
	v_max_f32_e32 v55, v5, v4
	v_max3_f32 v0, v0, v3, v55
	v_and_b32_e32 v55, 64, v199
	v_xor_b32_e32 v3, 32, v199
	v_add_u32_e32 v55, 64, v55
	v_cmp_lt_i32_e32 vcc, v3, v55
	s_nop 1
	v_cndmask_b32_e32 v3, v199, v3, vcc
	v_lshlrev_b32_e32 v3, 2, v3
	ds_bpermute_b32 v3, v3, v0
	s_waitcnt lgkmcnt(0)
	v_max3_f32 v3, v165, v0, v3
	v_sub_f32_e32 v0, v165, v3
	v_exp_f32_e32 v0, v0
	s_nop 0
	v_cmp_eq_f32_e32 vcc, 1.0, v0
	s_cmp_eq_u64 vcc, exec
	s_cbranch_scc1 .LBB0_131
	v_mul_f32_e32 v46, v46, v0
	v_mul_f32_e32 v47, v47, v0
	v_mul_f32_e32 v44, v44, v0
	v_mul_f32_e32 v45, v45, v0
	v_mul_f32_e32 v42, v42, v0
	v_mul_f32_e32 v43, v43, v0
	v_mul_f32_e32 v40, v40, v0
	v_mul_f32_e32 v41, v41, v0
	v_mul_f32_e32 v38, v38, v0
	v_mul_f32_e32 v39, v39, v0
	v_mul_f32_e32 v36, v36, v0
	v_mul_f32_e32 v37, v37, v0
	v_mul_f32_e32 v34, v34, v0
	v_mul_f32_e32 v35, v35, v0
	v_mul_f32_e32 v32, v32, v0
	v_mul_f32_e32 v33, v33, v0
	v_mul_f32_e32 v30, v30, v0
	v_mul_f32_e32 v31, v31, v0
	v_mul_f32_e32 v28, v28, v0
	v_mul_f32_e32 v29, v29, v0
	v_mul_f32_e32 v26, v26, v0
	v_mul_f32_e32 v27, v27, v0
	v_mul_f32_e32 v24, v24, v0
	v_mul_f32_e32 v25, v25, v0
	v_mul_f32_e32 v22, v22, v0
	v_mul_f32_e32 v23, v23, v0
	v_mul_f32_e32 v20, v20, v0
	v_mul_f32_e32 v21, v21, v0
	v_mul_f32_e32 v18, v18, v0
	v_mul_f32_e32 v19, v19, v0
	v_mul_f32_e32 v16, v16, v0
	v_mul_f32_e32 v17, v17, v0

.LBB0_132:
	s_waitcnt vmcnt(2)
	v_cvt_pk_bf16_f32 v4, v124, v125
	v_cvt_pk_bf16_f32 v5, v126, v127
	v_cvt_pk_bf16_f32 v6, v120, v121
	v_cvt_pk_bf16_f32 v7, v122, v123
	s_waitcnt vmcnt(0)
	v_cvt_pk_bf16_f32 v8, v116, v117
	v_cvt_pk_bf16_f32 v9, v118, v119
	v_cvt_pk_bf16_f32 v10, v112, v113
	v_cvt_pk_bf16_f32 v11, v114, v115
	ds_write_b128 v140, v[4:7] offset:18432
	ds_write_b128 v138, v[8:11] offset:61440
	v_cvt_pk_bf16_f32 v4, v124, v125
	v_cvt_pk_bf16_f32 v5, v126, v127
	v_cvt_pk_bf16_f32 v6, v120, v121
	v_cvt_pk_bf16_f32 v7, v122, v123
	s_and_b64 vcc, exec, s[24:25]
	v_cvt_pk_bf16_f32 v8, v116, v117
	v_cvt_pk_bf16_f32 v9, v118, v119
	v_cvt_pk_bf16_f32 v10, v112, v113
	v_cvt_pk_bf16_f32 v11, v114, v115
	ds_write_b128 v140, v[4:7] offset:27648
	ds_write_b128 v131, v[8:11] offset:36864
	s_waitcnt lgkmcnt(0)
	s_barrier
	s_cbranch_vccnz .LBB0_136
	ds_read_b128 v[4:7], v139 offset:18432
	s_waitcnt lgkmcnt(0)
	v_mfma_f32_32x32x16_bf16 v[48:63], v[4:7], v[96:99], 0
	ds_read_b128 v[4:7], v139 offset:23040
	s_waitcnt lgkmcnt(0)
	v_mfma_f32_32x32x16_bf16 v[64:79], v[4:7], v[96:99], 0
	ds_read_b128 v[4:7], v139 offset:18464
	s_waitcnt lgkmcnt(0)
	v_mfma_f32_32x32x16_bf16 v[48:63], v[4:7], v[100:103], v[48:63]
	ds_read_b128 v[4:7], v139 offset:23072
	s_waitcnt lgkmcnt(0)
	v_mfma_f32_32x32x16_bf16 v[64:79], v[4:7], v[100:103], v[64:79]
	ds_read_b128 v[4:7], v139 offset:18496
	s_waitcnt lgkmcnt(0)
	v_mfma_f32_32x32x16_bf16 v[48:63], v[4:7], v[104:107], v[48:63]
	ds_read_b128 v[4:7], v139 offset:23104
	s_waitcnt lgkmcnt(0)
	v_mfma_f32_32x32x16_bf16 v[64:79], v[4:7], v[104:107], v[64:79]
	ds_read_b128 v[4:7], v139 offset:23136
	s_waitcnt lgkmcnt(0)
	v_mfma_f32_32x32x16_bf16 v[64:79], v[4:7], v[108:111], v[64:79]
	ds_read_b128 v[6:9], v139 offset:18528
	s_waitcnt lgkmcnt(0)
	v_mfma_f32_32x32x16_bf16 v[48:63], v[6:9], v[108:111], v[48:63]
	s_nop 8
	v_mul_f32_e32 v65, 0x3fb8aa3b, v65
	v_mul_f32_e32 v67, 0x3fb8aa3b, v67
	v_mul_f32_e32 v66, 0x3fb8aa3b, v66
	v_mul_f32_e32 v64, 0x3fb8aa3b, v64
	v_mul_f32_e32 v68, 0x3fb8aa3b, v68
	v_mul_f32_e32 v13, 0x3fb8aa3b, v75
	v_mul_f32_e32 v15, 0x3fb8aa3b, v74
	v_mul_f32_e32 v49, 0x3fb8aa3b, v49
	v_mul_f32_e32 v6, 0x3fb8aa3b, v63
	v_mul_f32_e32 v63, 0x3fb8aa3b, v69
	v_mul_f32_e32 v51, 0x3fb8aa3b, v51
	v_mul_f32_e32 v50, 0x3fb8aa3b, v50
	v_mul_f32_e32 v69, 0x3fb8aa3b, v48
	v_max_f32_e32 v0, v49, v65
	v_mul_f32_e32 v53, 0x3fb8aa3b, v53
	v_mul_f32_e32 v52, 0x3fb8aa3b, v52
	v_max3_f32 v0, v69, v64, v0
	v_max_f32_e32 v4, v50, v66
	v_max_f32_e32 v48, v51, v67
	v_mul_f32_e32 v8, 0x3fb8aa3b, v62
	v_mul_f32_e32 v10, 0x3fb8aa3b, v61
	v_mul_f32_e32 v61, 0x3fb8aa3b, v71
	v_mul_f32_e32 v55, 0x3fb8aa3b, v55
	v_mul_f32_e32 v62, 0x3fb8aa3b, v70
	v_mul_f32_e32 v54, 0x3fb8aa3b, v54
	v_max3_f32 v0, v0, v4, v48
	v_max_f32_e32 v4, v52, v68
	v_max_f32_e32 v48, v53, v63
	v_mul_f32_e32 v12, 0x3fb8aa3b, v60
	v_mul_f32_e32 v14, 0x3fb8aa3b, v59
	v_mul_f32_e32 v59, 0x3fb8aa3b, v73
	v_mul_f32_e32 v57, 0x3fb8aa3b, v57
	v_mul_f32_e32 v60, 0x3fb8aa3b, v72
	v_mul_f32_e32 v56, 0x3fb8aa3b, v56
	v_max3_f32 v0, v0, v4, v48
	v_max_f32_e32 v4, v54, v62
	v_max_f32_e32 v48, v55, v61
	v_mul_f32_e32 v58, 0x3fb8aa3b, v58
	v_max3_f32 v0, v0, v4, v48
	v_max_f32_e32 v4, v56, v60
	v_max_f32_e32 v48, v57, v59
	v_mul_f32_e32 v9, 0x3fb8aa3b, v77
	v_mul_f32_e32 v11, 0x3fb8aa3b, v76
	v_max3_f32 v0, v0, v4, v48
	v_max_f32_e32 v4, v58, v15
	v_max_f32_e32 v48, v14, v13
	v_mul_f32_e32 v5, 0x3fb8aa3b, v79
	v_mul_f32_e32 v7, 0x3fb8aa3b, v78
	v_max3_f32 v0, v0, v4, v48
	v_max_f32_e32 v4, v12, v11
	v_max_f32_e32 v48, v10, v9
	v_max3_f32 v0, v0, v4, v48
	v_max_f32_e32 v4, v8, v7
	v_max_f32_e32 v48, v6, v5
	v_max3_f32 v0, v0, v4, v48
	v_and_b32_e32 v48, 64, v199
	v_xor_b32_e32 v4, 32, v199
	v_add_u32_e32 v48, 64, v48
	v_cmp_lt_i32_e32 vcc, v4, v48
	s_nop 1
	v_cndmask_b32_e32 v4, v199, v4, vcc
	v_lshlrev_b32_e32 v4, 2, v4
	ds_bpermute_b32 v48, v4, v0
	s_waitcnt lgkmcnt(0)
	v_max3_f32 v48, v3, v0, v48
	v_sub_f32_e32 v0, v3, v48
	v_exp_f32_e32 v0, v0
	s_nop 0
	v_cmp_eq_f32_e32 vcc, 1.0, v0
	s_cmp_eq_u64 vcc, exec
	s_cbranch_scc1 .LBB0_135
	v_mul_f32_e32 v46, v46, v0
	v_mul_f32_e32 v47, v47, v0
	v_mul_f32_e32 v44, v44, v0
	v_mul_f32_e32 v45, v45, v0
	v_mul_f32_e32 v42, v42, v0
	v_mul_f32_e32 v43, v43, v0
	v_mul_f32_e32 v40, v40, v0
	v_mul_f32_e32 v41, v41, v0
	v_mul_f32_e32 v38, v38, v0
	v_mul_f32_e32 v39, v39, v0
	v_mul_f32_e32 v36, v36, v0
	v_mul_f32_e32 v37, v37, v0
	v_mul_f32_e32 v34, v34, v0
	v_mul_f32_e32 v35, v35, v0
	v_mul_f32_e32 v32, v32, v0
	v_mul_f32_e32 v33, v33, v0
	v_mul_f32_e32 v30, v30, v0
	v_mul_f32_e32 v31, v31, v0
	v_mul_f32_e32 v28, v28, v0
	v_mul_f32_e32 v29, v29, v0
	v_mul_f32_e32 v26, v26, v0
	v_mul_f32_e32 v27, v27, v0
	v_mul_f32_e32 v24, v24, v0
	v_mul_f32_e32 v25, v25, v0
	v_mul_f32_e32 v22, v22, v0
	v_mul_f32_e32 v23, v23, v0
	v_mul_f32_e32 v20, v20, v0
	v_mul_f32_e32 v21, v21, v0
	v_mul_f32_e32 v18, v18, v0
	v_mul_f32_e32 v19, v19, v0
	v_mul_f32_e32 v16, v16, v0
	v_mul_f32_e32 v17, v17, v0

.LBB0_167:
	s_nop 10
	v_mul_f32_e64 v64, v64, s68
	v_mul_f32_e64 v65, v65, s68
	v_mul_f32_e64 v14, v66, s68
	v_mul_f32_e64 v15, v67, s68
	v_mul_f32_e64 v12, v68, s68
	v_mul_f32_e64 v13, v69, s68
	v_mul_f32_e64 v10, v70, s68
	v_mul_f32_e64 v11, v71, s68
	v_mul_f32_e64 v8, v72, s68
	v_mul_f32_e64 v9, v73, s68
	v_mul_f32_e64 v6, v74, s68
	v_mul_f32_e64 v7, v75, s68
	v_mul_f32_e64 v4, v76, s68
	v_mul_f32_e64 v5, v77, s68
	v_mul_f32_e64 v2, v78, s68
	v_mul_f32_e64 v3, v79, s68
.LBB0_168:
	v_mul_f32_e32 v76, 0x3fb8aa3b, v49
	v_max_f32_e32 v0, v65, v65
	v_mul_f32_e32 v77, 0x3fb8aa3b, v48
	v_mul_f32_e32 v75, 0x3fb8aa3b, v50
	v_mul_f32_e32 v74, 0x3fb8aa3b, v51
	v_mul_f32_e32 v73, 0x3fb8aa3b, v52
	v_mul_f32_e32 v71, 0x3fb8aa3b, v53
	v_max_f32_e32 v0, v76, v0
	v_max_f32_e32 v52, v14, v14
	v_max_f32_e32 v53, v15, v15
	v_max3_f32 v0, v77, v64, v0
	v_max_f32_e32 v52, v75, v52
	v_max_f32_e32 v53, v74, v53
	v_max3_f32 v0, v0, v52, v53
	v_max_f32_e32 v52, v12, v12
	v_max_f32_e32 v53, v13, v13
	v_max_f32_e32 v52, v73, v52
	v_max_f32_e32 v53, v71, v53
	v_mul_f32_e32 v69, 0x3fb8aa3b, v54
	v_mul_f32_e32 v67, 0x3fb8aa3b, v55
	v_max3_f32 v0, v0, v52, v53
	v_max_f32_e32 v52, v10, v10
	v_max_f32_e32 v53, v11, v11
	v_max_f32_e32 v52, v69, v52
	v_max_f32_e32 v53, v67, v53
	v_mul_f32_e32 v66, 0x3fb8aa3b, v56
	v_mul_f32_e32 v68, 0x3fb8aa3b, v57
	v_max3_f32 v0, v0, v52, v53
	v_max_f32_e32 v52, v8, v8
	v_max_f32_e32 v53, v9, v9
	v_max_f32_e32 v52, v66, v52
	v_max_f32_e32 v53, v68, v53
	v_mul_f32_e32 v70, 0x3fb8aa3b, v58
	v_mul_f32_e32 v72, 0x3fb8aa3b, v59
	v_max3_f32 v0, v0, v52, v53
	v_max_f32_e32 v52, v6, v6
	v_max_f32_e32 v53, v7, v7
	v_max_f32_e32 v52, v70, v52
	v_max_f32_e32 v53, v72, v53
	v_mul_f32_e32 v51, 0x3fb8aa3b, v60
	v_mul_f32_e32 v50, 0x3fb8aa3b, v61
	v_max3_f32 v0, v0, v52, v53
	v_max_f32_e32 v52, v4, v4
	v_max_f32_e32 v53, v5, v5
	v_max_f32_e32 v52, v51, v52
	v_max_f32_e32 v53, v50, v53
	v_mul_f32_e32 v49, 0x3fb8aa3b, v62
	v_mul_f32_e32 v48, 0x3fb8aa3b, v63
	v_max3_f32 v0, v0, v52, v53
	v_max_f32_e32 v52, v2, v2
	v_max_f32_e32 v53, v3, v3
	v_max_f32_e32 v52, v49, v52
	v_max_f32_e32 v53, v48, v53
	v_max3_f32 v0, v0, v52, v53
	v_and_b32_e32 v53, 64, v199
	v_xor_b32_e32 v52, 32, v199
	v_add_u32_e32 v53, 64, v53
	v_cmp_lt_i32_e32 vcc, v52, v53
	s_nop 1
	v_cndmask_b32_e32 v52, v199, v52, vcc
	v_lshlrev_b32_e32 v52, 2, v52
	ds_bpermute_b32 v52, v52, v0
	s_waitcnt lgkmcnt(0)
	v_max3_f32 v52, v118, v0, v52
	v_sub_f32_e32 v0, v118, v52
	v_exp_f32_e32 v0, v0
	s_nop 0
	v_cmp_eq_f32_e32 vcc, 1.0, v0
	s_cmp_eq_u64 vcc, exec
	s_cbranch_scc1 .LBB0_170
	v_mul_f32_e32 v46, v46, v0
	v_mul_f32_e32 v47, v47, v0
	v_mul_f32_e32 v44, v44, v0
	v_mul_f32_e32 v45, v45, v0
	v_mul_f32_e32 v42, v42, v0
	v_mul_f32_e32 v43, v43, v0
	v_mul_f32_e32 v40, v40, v0
	v_mul_f32_e32 v41, v41, v0
	v_mul_f32_e32 v38, v38, v0
	v_mul_f32_e32 v39, v39, v0
	v_mul_f32_e32 v36, v36, v0
	v_mul_f32_e32 v37, v37, v0
	v_mul_f32_e32 v34, v34, v0
	v_mul_f32_e32 v35, v35, v0
	v_mul_f32_e32 v32, v32, v0
	v_mul_f32_e32 v33, v33, v0
	v_mul_f32_e32 v30, v30, v0
	v_mul_f32_e32 v31, v31, v0
	v_mul_f32_e32 v28, v28, v0
	v_mul_f32_e32 v29, v29, v0
	v_mul_f32_e32 v26, v26, v0
	v_mul_f32_e32 v27, v27, v0
	v_mul_f32_e32 v24, v24, v0
	v_mul_f32_e32 v25, v25, v0
	v_mul_f32_e32 v22, v22, v0
	v_mul_f32_e32 v23, v23, v0
	v_mul_f32_e32 v20, v20, v0
	v_mul_f32_e32 v21, v21, v0
	v_mul_f32_e32 v18, v18, v0
	v_mul_f32_e32 v19, v19, v0
	v_mul_f32_e32 v16, v16, v0
	v_mul_f32_e32 v17, v17, v0

.LBB0_259:
	s_or_b32 s16, s4, s48
	s_ashr_i32 s17, s16, 31
	s_and_b64 vcc, exec, s[40:41]
	v_lshlrev_b32_e32 v158, 1, v138
	s_cbranch_vccz .LBB0_263
	v_and_b32_e32 v159, 0x7cf, v173
	v_cmp_gt_i32_e32 vcc, s94, v173
	v_mov_b32_e32 v165, v1
	v_lshl_add_u64 v[162:163], s[16:17], 1, v[162:163]
	v_cndmask_b32_e32 v159, v167, v159, vcc
	v_lshlrev_b32_e32 v164, 7, v159
	v_lshl_add_u64 v[178:179], v[142:143], 0, v[164:165]
	global_load_dwordx4 v[174:177], v[178:179], off
	s_nop 0
	global_load_dwordx4 v[178:181], v[178:179], off offset:16
	v_lshl_add_u64 v[164:165], v[140:141], 0, v[164:165]
	global_load_dwordx4 v[182:185], v[164:165], off
	global_load_dwordx4 v[186:189], v[164:165], off offset:16
	v_or_b32_e32 v240, s20, v168
	v_cmp_gt_i32_e32 vcc, s94, v240
	v_and_b32_e32 v240, 0x7ff, v240
	v_mov_b32_e32 v241, 0
	v_cndmask_b32_e32 v240, v169, v240, vcc
	v_lshlrev_b32_e32 v240, 7, v240
	v_lshl_add_u64 v[242:243], v[142:143], 0, v[240:241]
	v_lshl_add_u64 v[244:245], v[140:141], 0, v[240:241]
	global_load_dwordx4 v[224:227], v[242:243], off
	global_load_dwordx4 v[228:231], v[242:243], off offset:16
	global_load_dwordx4 v[232:235], v[244:245], off
	global_load_dwordx4 v[236:239], v[244:245], off offset:16
	v_mov_b32_e32 v159, v1
	v_lshl_add_u64 v[190:191], v[162:163], 0, v[158:159]
	v_cmp_ne_u64_e32 vcc, 0, v[160:161]
	s_waitcnt vmcnt(4)
	v_mul_f32_e32 v162, v120, v176
	v_mul_f32_e32 v163, v121, v177
	v_mul_f32_e32 v164, v118, v174
	v_mul_f32_e32 v165, v119, v175
	v_mul_f32_e32 v192, v116, v180
	v_mul_f32_e32 v193, v117, v181
	v_mul_f32_e32 v206, v114, v178
	v_mul_f32_e32 v207, v115, v179
	v_mul_f32_e32 v176, v128, v176
	v_mul_f32_e32 v177, v129, v177
	v_mul_f32_e32 v174, v126, v174
	v_mul_f32_e32 v175, v127, v175
	v_mul_f32_e32 v180, v124, v180
	v_mul_f32_e32 v181, v125, v181
	v_mul_f32_e32 v178, v122, v178
	v_mul_f32_e32 v179, v123, v179
	v_fma_f32 v128, v128, v184, -v162
	v_fma_f32 v129, v129, v185, -v163
	v_fma_f32 v126, v126, v182, -v164
	v_fma_f32 v127, v127, v183, -v165
	v_fma_f32 v124, v124, v188, -v192
	v_fma_f32 v125, v125, v189, -v193
	v_fma_f32 v122, v122, v186, -v206
	v_fma_f32 v123, v123, v187, -v207
	v_fma_f32 v120, v120, v184, v176
	v_fma_f32 v121, v121, v185, v177
	v_fma_f32 v118, v118, v182, v174
	v_fma_f32 v119, v119, v183, v175
	v_fma_f32 v116, v116, v188, v180
	v_fma_f32 v117, v117, v189, v181
	v_fma_f32 v114, v114, v186, v178
	v_fma_f32 v115, v115, v187, v179
	v_cvt_pk_bf16_f32 v162, v126, v127
	v_cvt_pk_bf16_f32 v163, v128, v129
	v_cvt_pk_bf16_f32 v164, v122, v123
	v_cvt_pk_bf16_f32 v165, v124, v125
	v_cvt_pk_bf16_f32 v174, v118, v119
	v_cvt_pk_bf16_f32 v175, v120, v121
	s_nop 0
	v_cvt_pk_bf16_f32 v176, v114, v115
	v_cvt_pk_bf16_f32 v177, v116, v117
	global_store_dwordx4 v[190:191], v[162:165], off
	global_store_dwordx4 v[190:191], v[174:177], off offset:64
	s_and_saveexec_b64 s[0:1], vcc
	s_cbranch_execz .LBB0_262
	v_lshl_add_u64 v[160:161], s[16:17], 2, v[160:161]
	v_lshlrev_b32_e32 v162, 2, v138
	v_mov_b32_e32 v163, v1
	v_lshl_add_u64 v[160:161], v[160:161], 0, v[162:163]
	global_store_dwordx4 v[160:161], v[126:129], off offset:-4096
	global_store_dwordx4 v[160:161], v[122:125], off offset:-4080
	global_store_dwordx4 v[160:161], v[118:121], off offset:-3968
	global_store_dwordx4 v[160:161], v[114:117], off offset:-3952

.LBB0_275:
	s_and_b64 vcc, exec, s[4:5]
	s_cbranch_vccz .LBB0_279
	v_and_b32_e32 v118, 0x7df, v122
	v_cmp_gt_i32_e32 vcc, s94, v122
	v_mov_b32_e32 v127, v1
	v_lshl_add_u64 v[116:117], s[16:17], 1, v[116:117]
	v_cndmask_b32_e32 v118, v169, v118, vcc
	v_lshlrev_b32_e32 v126, 7, v118
	v_lshl_add_u64 v[122:123], v[142:143], 0, v[126:127]
	s_nop 0
	v_lshl_add_u64 v[160:161], v[140:141], 0, v[126:127]
	s_nop 0
	v_or_b32_e32 v240, s20, v170
	v_cmp_gt_i32_e32 vcc, s94, v240
	v_and_b32_e32 v240, 0x7ff, v240
	v_mov_b32_e32 v241, 0
	v_cndmask_b32_e32 v240, v167, v240, vcc
	v_lshlrev_b32_e32 v240, 7, v240
	v_lshl_add_u64 v[242:243], v[142:143], 0, v[240:241]
	v_lshl_add_u64 v[244:245], v[140:141], 0, v[240:241]
	global_load_dwordx4 v[208:211], v[242:243], off
	global_load_dwordx4 v[212:215], v[242:243], off offset:16
	global_load_dwordx4 v[216:219], v[244:245], off
	global_load_dwordx4 v[220:223], v[244:245], off offset:16
	v_mov_b32_e32 v159, v1
	v_lshl_add_u64 v[164:165], v[116:117], 0, v[158:159]
	v_cmp_ne_u64_e32 vcc, 0, v[114:115]
	s_waitcnt vmcnt(6)
	v_mul_f32_e32 v116, v104, v226
	v_mul_f32_e32 v117, v105, v227
	v_mul_f32_e32 v174, v102, v224
	v_mul_f32_e32 v175, v103, v225
	v_mul_f32_e32 v176, v100, v230
	v_mul_f32_e32 v177, v101, v231
	v_mul_f32_e32 v178, v98, v228
	v_mul_f32_e32 v179, v99, v229
	v_mul_f32_e32 v120, v112, v226
	v_mul_f32_e32 v121, v113, v227
	v_mul_f32_e32 v118, v110, v224
	v_mul_f32_e32 v119, v111, v225
	v_mul_f32_e32 v124, v108, v230
	v_mul_f32_e32 v125, v109, v231
	v_mul_f32_e32 v122, v106, v228
	v_mul_f32_e32 v123, v107, v229
	v_fma_f32 v112, v112, v234, -v116
	v_fma_f32 v113, v113, v235, -v117
	v_fma_f32 v110, v110, v232, -v174
	v_fma_f32 v111, v111, v233, -v175
	v_fma_f32 v108, v108, v238, -v176
	v_fma_f32 v109, v109, v239, -v177
	v_fma_f32 v106, v106, v236, -v178
	v_fma_f32 v107, v107, v237, -v179
	v_fma_f32 v104, v104, v234, v120
	v_fma_f32 v105, v105, v235, v121
	v_fma_f32 v102, v102, v232, v118
	v_fma_f32 v103, v103, v233, v119
	v_fma_f32 v100, v100, v238, v124
	v_fma_f32 v101, v101, v239, v125
	v_fma_f32 v98, v98, v236, v122
	v_fma_f32 v99, v99, v237, v123
	v_cvt_pk_bf16_f32 v116, v110, v111
	v_cvt_pk_bf16_f32 v117, v112, v113
	v_cvt_pk_bf16_f32 v118, v106, v107
	v_cvt_pk_bf16_f32 v119, v108, v109
	v_cvt_pk_bf16_f32 v120, v102, v103
	v_cvt_pk_bf16_f32 v121, v104, v105
	s_nop 0
	v_cvt_pk_bf16_f32 v122, v98, v99
	v_cvt_pk_bf16_f32 v123, v100, v101
	global_store_dwordx4 v[164:165], v[116:119], off
	global_store_dwordx4 v[164:165], v[120:123], off offset:64
	s_and_saveexec_b64 s[0:1], vcc
	s_cbranch_execz .LBB0_278
	v_lshl_add_u64 v[114:115], s[16:17], 2, v[114:115]
	v_lshlrev_b32_e32 v116, 2, v138
	v_mov_b32_e32 v117, v1
	v_lshl_add_u64 v[114:115], v[114:115], 0, v[116:117]
	global_store_dwordx4 v[114:115], v[110:113], off offset:-4096
	global_store_dwordx4 v[114:115], v[106:109], off offset:-4080
	global_store_dwordx4 v[114:115], v[102:105], off offset:-3968
	global_store_dwordx4 v[114:115], v[98:101], off offset:-3952

.LBB0_291:
	s_and_b64 vcc, exec, s[4:5]
	s_cbranch_vccz .LBB0_295
	v_and_b32_e32 v102, 0x7ef, v106
	v_cmp_gt_i32_e32 vcc, s94, v106
	v_mov_b32_e32 v111, v1
	v_lshl_add_u64 v[100:101], s[16:17], 1, v[100:101]
	v_cndmask_b32_e32 v102, v167, v102, vcc
	v_lshlrev_b32_e32 v110, 7, v102
	v_lshl_add_u64 v[106:107], v[142:143], 0, v[110:111]
	s_nop 0
	v_lshl_add_u64 v[114:115], v[140:141], 0, v[110:111]
	s_nop 0
	v_or_b32_e32 v240, s20, v171
	v_cmp_gt_i32_e32 vcc, s94, v240
	v_and_b32_e32 v240, 0x7ff, v240
	v_mov_b32_e32 v241, 0
	v_cndmask_b32_e32 v240, v169, v240, vcc
	v_lshlrev_b32_e32 v240, 7, v240
	v_lshl_add_u64 v[242:243], v[142:143], 0, v[240:241]
	v_lshl_add_u64 v[244:245], v[140:141], 0, v[240:241]
	global_load_dwordx4 v[224:227], v[242:243], off
	global_load_dwordx4 v[228:231], v[242:243], off offset:16
	global_load_dwordx4 v[232:235], v[244:245], off
	global_load_dwordx4 v[236:239], v[244:245], off offset:16
	v_mov_b32_e32 v159, v1
	v_lshl_add_u64 v[118:119], v[100:101], 0, v[158:159]
	v_cmp_ne_u64_e32 vcc, 0, v[98:99]
	s_waitcnt vmcnt(6)
	v_mul_f32_e32 v100, v88, v210
	v_mul_f32_e32 v101, v89, v211
	v_mul_f32_e32 v120, v86, v208
	v_mul_f32_e32 v121, v87, v209
	v_mul_f32_e32 v122, v84, v214
	v_mul_f32_e32 v123, v85, v215
	v_mul_f32_e32 v124, v82, v212
	v_mul_f32_e32 v125, v83, v213
	v_mul_f32_e32 v104, v96, v210
	v_mul_f32_e32 v105, v97, v211
	v_mul_f32_e32 v102, v94, v208
	v_mul_f32_e32 v103, v95, v209
	v_mul_f32_e32 v108, v92, v214
	v_mul_f32_e32 v109, v93, v215
	v_mul_f32_e32 v106, v90, v212
	v_mul_f32_e32 v107, v91, v213
	v_fma_f32 v96, v96, v218, -v100
	v_fma_f32 v97, v97, v219, -v101
	v_fma_f32 v94, v94, v216, -v120
	v_fma_f32 v95, v95, v217, -v121
	v_fma_f32 v92, v92, v222, -v122
	v_fma_f32 v93, v93, v223, -v123
	v_fma_f32 v90, v90, v220, -v124
	v_fma_f32 v91, v91, v221, -v125
	v_fma_f32 v88, v88, v218, v104
	v_fma_f32 v89, v89, v219, v105
	v_fma_f32 v86, v86, v216, v102
	v_fma_f32 v87, v87, v217, v103
	v_fma_f32 v84, v84, v222, v108
	v_fma_f32 v85, v85, v223, v109
	v_fma_f32 v82, v82, v220, v106
	v_fma_f32 v83, v83, v221, v107
	v_cvt_pk_bf16_f32 v100, v94, v95
	v_cvt_pk_bf16_f32 v101, v96, v97
	v_cvt_pk_bf16_f32 v102, v90, v91
	v_cvt_pk_bf16_f32 v103, v92, v93
	v_cvt_pk_bf16_f32 v104, v86, v87
	v_cvt_pk_bf16_f32 v105, v88, v89
	s_nop 0
	v_cvt_pk_bf16_f32 v106, v82, v83
	v_cvt_pk_bf16_f32 v107, v84, v85
	global_store_dwordx4 v[118:119], v[100:103], off
	global_store_dwordx4 v[118:119], v[104:107], off offset:64
	s_and_saveexec_b64 s[0:1], vcc
	s_cbranch_execz .LBB0_294
	v_lshl_add_u64 v[98:99], s[16:17], 2, v[98:99]
	v_lshlrev_b32_e32 v100, 2, v138
	v_mov_b32_e32 v101, v1
	v_lshl_add_u64 v[98:99], v[98:99], 0, v[100:101]
	global_store_dwordx4 v[98:99], v[94:97], off offset:-4096
	global_store_dwordx4 v[98:99], v[90:93], off offset:-4080
	global_store_dwordx4 v[98:99], v[86:89], off offset:-3968
	global_store_dwordx4 v[98:99], v[82:85], off offset:-3952

.LBB0_307:
	s_and_b64 vcc, exec, s[4:5]
	s_cbranch_vccz .LBB0_311
	v_and_b32_e32 v86, 0x7ff, v90
	v_cmp_gt_i32_e32 vcc, s94, v90
	v_mov_b32_e32 v95, v1
	v_lshl_add_u64 v[84:85], s[16:17], 1, v[84:85]
	v_cndmask_b32_e32 v86, v169, v86, vcc
	v_lshlrev_b32_e32 v94, 7, v86
	v_lshl_add_u64 v[90:91], v[142:143], 0, v[94:95]
	s_nop 0
	v_lshl_add_u64 v[98:99], v[140:141], 0, v[94:95]
	s_nop 0
	v_or_b32_e32 v240, s20, v139
	v_add_u32_e32 v240, 0x80, v240
	v_cmp_gt_i32_e32 vcc, s94, v240
	v_and_b32_e32 v240, 0x7ff, v240
	v_mov_b32_e32 v241, 0
	v_cndmask_b32_e32 v240, v167, v240, vcc
	v_lshlrev_b32_e32 v240, 7, v240
	v_lshl_add_u64 v[242:243], v[142:143], 0, v[240:241]
	v_lshl_add_u64 v[244:245], v[140:141], 0, v[240:241]
	global_load_dwordx4 v[208:211], v[242:243], off
	global_load_dwordx4 v[212:215], v[242:243], off offset:16
	global_load_dwordx4 v[216:219], v[244:245], off
	global_load_dwordx4 v[220:223], v[244:245], off offset:16
	v_mov_b32_e32 v159, v1
	v_lshl_add_u64 v[102:103], v[84:85], 0, v[158:159]
	v_cmp_ne_u64_e32 vcc, 0, v[82:83]
	s_waitcnt vmcnt(6)
	v_mul_f32_e32 v84, v72, v226
	v_mul_f32_e32 v85, v73, v227
	v_mul_f32_e32 v104, v70, v224
	v_mul_f32_e32 v105, v71, v225
	v_mul_f32_e32 v106, v68, v230
	v_mul_f32_e32 v107, v69, v231
	v_mul_f32_e32 v108, v66, v228
	v_mul_f32_e32 v109, v67, v229
	v_mul_f32_e32 v88, v80, v226
	v_mul_f32_e32 v89, v81, v227
	v_mul_f32_e32 v86, v78, v224
	v_mul_f32_e32 v87, v79, v225
	v_mul_f32_e32 v92, v76, v230
	v_mul_f32_e32 v93, v77, v231
	v_mul_f32_e32 v90, v74, v228
	v_mul_f32_e32 v91, v75, v229
	v_fma_f32 v80, v80, v234, -v84
	v_fma_f32 v81, v81, v235, -v85
	v_fma_f32 v78, v78, v232, -v104
	v_fma_f32 v79, v79, v233, -v105
	v_fma_f32 v76, v76, v238, -v106
	v_fma_f32 v77, v77, v239, -v107
	v_fma_f32 v74, v74, v236, -v108
	v_fma_f32 v75, v75, v237, -v109
	v_fma_f32 v72, v72, v234, v88
	v_fma_f32 v73, v73, v235, v89
	v_fma_f32 v70, v70, v232, v86
	v_fma_f32 v71, v71, v233, v87
	v_fma_f32 v68, v68, v238, v92
	v_fma_f32 v69, v69, v239, v93
	v_fma_f32 v66, v66, v236, v90
	v_fma_f32 v67, v67, v237, v91
	v_cvt_pk_bf16_f32 v84, v78, v79
	v_cvt_pk_bf16_f32 v85, v80, v81
	v_cvt_pk_bf16_f32 v86, v74, v75
	v_cvt_pk_bf16_f32 v87, v76, v77
	v_cvt_pk_bf16_f32 v88, v70, v71
	v_cvt_pk_bf16_f32 v89, v72, v73
	s_nop 0
	v_cvt_pk_bf16_f32 v90, v66, v67
	v_cvt_pk_bf16_f32 v91, v68, v69
	global_store_dwordx4 v[102:103], v[84:87], off
	global_store_dwordx4 v[102:103], v[88:91], off offset:64
	s_and_saveexec_b64 s[0:1], vcc
	s_cbranch_execz .LBB0_310
	v_lshl_add_u64 v[82:83], s[16:17], 2, v[82:83]
	v_lshlrev_b32_e32 v84, 2, v138
	v_mov_b32_e32 v85, v1
	v_lshl_add_u64 v[82:83], v[82:83], 0, v[84:85]
	global_store_dwordx4 v[82:83], v[78:81], off offset:-4096
	global_store_dwordx4 v[82:83], v[74:77], off offset:-4080
	global_store_dwordx4 v[82:83], v[70:73], off offset:-3968
	global_store_dwordx4 v[82:83], v[66:69], off offset:-3952

.LBB0_323:
	s_and_b64 vcc, exec, s[4:5]
	s_cbranch_vccz .LBB0_327
	v_and_b32_e32 v70, 0x7cf, v74
	v_cmp_gt_i32_e32 vcc, s94, v74
	v_mov_b32_e32 v79, v1
	v_lshl_add_u64 v[68:69], s[16:17], 1, v[68:69]
	v_cndmask_b32_e32 v70, v167, v70, vcc
	v_lshlrev_b32_e32 v78, 7, v70
	v_lshl_add_u64 v[74:75], v[142:143], 0, v[78:79]
	s_nop 0
	v_lshl_add_u64 v[82:83], v[140:141], 0, v[78:79]
	s_nop 0
	v_or_b32_e32 v240, s20, v168
	v_cmp_gt_i32_e32 vcc, s94, v240
	v_and_b32_e32 v240, 0x7ff, v240
	v_mov_b32_e32 v241, 0
	v_cndmask_b32_e32 v240, v169, v240, vcc
	v_lshlrev_b32_e32 v240, 7, v240
	v_lshl_add_u64 v[242:243], v[142:143], 0, v[240:241]
	v_lshl_add_u64 v[244:245], v[140:141], 0, v[240:241]
	global_load_dwordx4 v[224:227], v[242:243], off
	global_load_dwordx4 v[228:231], v[242:243], off offset:16
	global_load_dwordx4 v[232:235], v[244:245], off
	global_load_dwordx4 v[236:239], v[244:245], off offset:16
	v_mov_b32_e32 v159, v1
	v_lshl_add_u64 v[86:87], v[68:69], 0, v[158:159]
	v_cmp_ne_u64_e32 vcc, 0, v[66:67]
	s_waitcnt vmcnt(6)
	v_mul_f32_e32 v68, v56, v210
	v_mul_f32_e32 v69, v57, v211
	v_mul_f32_e32 v88, v54, v208
	v_mul_f32_e32 v89, v55, v209
	v_mul_f32_e32 v90, v52, v214
	v_mul_f32_e32 v91, v53, v215
	v_mul_f32_e32 v92, v50, v212
	v_mul_f32_e32 v93, v51, v213
	v_mul_f32_e32 v72, v64, v210
	v_mul_f32_e32 v73, v65, v211
	v_mul_f32_e32 v70, v62, v208
	v_mul_f32_e32 v71, v63, v209
	v_mul_f32_e32 v76, v60, v214
	v_mul_f32_e32 v77, v61, v215
	v_mul_f32_e32 v74, v58, v212
	v_mul_f32_e32 v75, v59, v213
	v_fma_f32 v64, v64, v218, -v68
	v_fma_f32 v65, v65, v219, -v69
	v_fma_f32 v62, v62, v216, -v88
	v_fma_f32 v63, v63, v217, -v89
	v_fma_f32 v60, v60, v222, -v90
	v_fma_f32 v61, v61, v223, -v91
	v_fma_f32 v58, v58, v220, -v92
	v_fma_f32 v59, v59, v221, -v93
	v_fma_f32 v56, v56, v218, v72
	v_fma_f32 v57, v57, v219, v73
	v_fma_f32 v54, v54, v216, v70
	v_fma_f32 v55, v55, v217, v71
	v_fma_f32 v52, v52, v222, v76
	v_fma_f32 v53, v53, v223, v77
	v_fma_f32 v50, v50, v220, v74
	v_fma_f32 v51, v51, v221, v75
	v_cvt_pk_bf16_f32 v68, v62, v63
	v_cvt_pk_bf16_f32 v69, v64, v65
	v_cvt_pk_bf16_f32 v70, v58, v59
	v_cvt_pk_bf16_f32 v71, v60, v61
	v_cvt_pk_bf16_f32 v72, v54, v55
	v_cvt_pk_bf16_f32 v73, v56, v57
	s_nop 0
	v_cvt_pk_bf16_f32 v74, v50, v51
	v_cvt_pk_bf16_f32 v75, v52, v53
	global_store_dwordx4 v[86:87], v[68:71], off
	global_store_dwordx4 v[86:87], v[72:75], off offset:64
	s_and_saveexec_b64 s[0:1], vcc
	s_cbranch_execz .LBB0_326
	v_lshl_add_u64 v[66:67], s[16:17], 2, v[66:67]
	v_lshlrev_b32_e32 v68, 2, v138
	v_mov_b32_e32 v69, v1
	v_lshl_add_u64 v[66:67], v[66:67], 0, v[68:69]
	global_store_dwordx4 v[66:67], v[62:65], off offset:-4096
	global_store_dwordx4 v[66:67], v[58:61], off offset:-4080
	global_store_dwordx4 v[66:67], v[54:57], off offset:-3968
	global_store_dwordx4 v[66:67], v[50:53], off offset:-3952

.LBB0_339:
	s_and_b64 vcc, exec, s[4:5]
	s_cbranch_vccz .LBB0_343
	v_and_b32_e32 v54, 0x7df, v58
	v_cmp_gt_i32_e32 vcc, s94, v58
	v_mov_b32_e32 v63, v1
	v_lshl_add_u64 v[52:53], s[16:17], 1, v[52:53]
	v_cndmask_b32_e32 v54, v169, v54, vcc
	v_lshlrev_b32_e32 v62, 7, v54
	v_lshl_add_u64 v[58:59], v[142:143], 0, v[62:63]
	s_nop 0
	v_lshl_add_u64 v[66:67], v[140:141], 0, v[62:63]
	s_nop 0
	v_or_b32_e32 v240, s20, v170
	v_cmp_gt_i32_e32 vcc, s94, v240
	v_and_b32_e32 v240, 0x7ff, v240
	v_mov_b32_e32 v241, 0
	v_cndmask_b32_e32 v240, v167, v240, vcc
	v_lshlrev_b32_e32 v240, 7, v240
	v_lshl_add_u64 v[242:243], v[142:143], 0, v[240:241]
	v_lshl_add_u64 v[244:245], v[140:141], 0, v[240:241]
	global_load_dwordx4 v[208:211], v[242:243], off
	global_load_dwordx4 v[212:215], v[242:243], off offset:16
	global_load_dwordx4 v[216:219], v[244:245], off
	global_load_dwordx4 v[220:223], v[244:245], off offset:16
	v_mov_b32_e32 v159, v1
	v_lshl_add_u64 v[70:71], v[52:53], 0, v[158:159]
	v_cmp_ne_u64_e32 vcc, 0, v[50:51]
	s_waitcnt vmcnt(6)
	v_mul_f32_e32 v52, v40, v226
	v_mul_f32_e32 v53, v41, v227
	v_mul_f32_e32 v72, v38, v224
	v_mul_f32_e32 v73, v39, v225
	v_mul_f32_e32 v74, v36, v230
	v_mul_f32_e32 v75, v37, v231
	v_mul_f32_e32 v76, v34, v228
	v_mul_f32_e32 v77, v35, v229
	v_mul_f32_e32 v56, v48, v226
	v_mul_f32_e32 v57, v49, v227
	v_mul_f32_e32 v54, v46, v224
	v_mul_f32_e32 v55, v47, v225
	v_mul_f32_e32 v60, v44, v230
	v_mul_f32_e32 v61, v45, v231
	v_mul_f32_e32 v58, v42, v228
	v_mul_f32_e32 v59, v43, v229
	v_fma_f32 v48, v48, v234, -v52
	v_fma_f32 v49, v49, v235, -v53
	v_fma_f32 v46, v46, v232, -v72
	v_fma_f32 v47, v47, v233, -v73
	v_fma_f32 v44, v44, v238, -v74
	v_fma_f32 v45, v45, v239, -v75
	v_fma_f32 v42, v42, v236, -v76
	v_fma_f32 v43, v43, v237, -v77
	v_fma_f32 v40, v40, v234, v56
	v_fma_f32 v41, v41, v235, v57
	v_fma_f32 v38, v38, v232, v54
	v_fma_f32 v39, v39, v233, v55
	v_fma_f32 v36, v36, v238, v60
	v_fma_f32 v37, v37, v239, v61
	v_fma_f32 v34, v34, v236, v58
	v_fma_f32 v35, v35, v237, v59
	v_cvt_pk_bf16_f32 v52, v46, v47
	v_cvt_pk_bf16_f32 v53, v48, v49
	v_cvt_pk_bf16_f32 v54, v42, v43
	v_cvt_pk_bf16_f32 v55, v44, v45
	v_cvt_pk_bf16_f32 v56, v38, v39
	v_cvt_pk_bf16_f32 v57, v40, v41
	s_nop 0
	v_cvt_pk_bf16_f32 v58, v34, v35
	v_cvt_pk_bf16_f32 v59, v36, v37
	global_store_dwordx4 v[70:71], v[52:55], off
	global_store_dwordx4 v[70:71], v[56:59], off offset:64
	s_and_saveexec_b64 s[0:1], vcc
	s_cbranch_execz .LBB0_342
	v_lshl_add_u64 v[50:51], s[16:17], 2, v[50:51]
	v_lshlrev_b32_e32 v52, 2, v138
	v_mov_b32_e32 v53, v1
	v_lshl_add_u64 v[50:51], v[50:51], 0, v[52:53]
	global_store_dwordx4 v[50:51], v[46:49], off offset:-4096
	global_store_dwordx4 v[50:51], v[42:45], off offset:-4080
	global_store_dwordx4 v[50:51], v[38:41], off offset:-3968
	global_store_dwordx4 v[50:51], v[34:37], off offset:-3952

.LBB0_355:
	s_and_b64 vcc, exec, s[4:5]
	s_cbranch_vccz .LBB0_359
	v_and_b32_e32 v38, 0x7ef, v42
	v_cmp_gt_i32_e32 vcc, s94, v42
	v_mov_b32_e32 v47, v1
	v_lshl_add_u64 v[36:37], s[16:17], 1, v[36:37]
	v_cndmask_b32_e32 v38, v167, v38, vcc
	v_lshlrev_b32_e32 v46, 7, v38
	v_lshl_add_u64 v[42:43], v[142:143], 0, v[46:47]
	s_nop 0
	v_lshl_add_u64 v[50:51], v[140:141], 0, v[46:47]
	s_nop 0
	v_or_b32_e32 v240, s20, v171
	v_cmp_gt_i32_e32 vcc, s94, v240
	v_and_b32_e32 v240, 0x7ff, v240
	v_mov_b32_e32 v241, 0
	v_cndmask_b32_e32 v240, v169, v240, vcc
	v_lshlrev_b32_e32 v240, 7, v240
	v_lshl_add_u64 v[242:243], v[142:143], 0, v[240:241]
	v_lshl_add_u64 v[244:245], v[140:141], 0, v[240:241]
	global_load_dwordx4 v[224:227], v[242:243], off
	global_load_dwordx4 v[228:231], v[242:243], off offset:16
	global_load_dwordx4 v[232:235], v[244:245], off
	global_load_dwordx4 v[236:239], v[244:245], off offset:16
	v_mov_b32_e32 v159, v1
	v_lshl_add_u64 v[54:55], v[36:37], 0, v[158:159]
	v_cmp_ne_u64_e32 vcc, 0, v[34:35]
	s_waitcnt vmcnt(6)
	v_mul_f32_e32 v36, v24, v210
	v_mul_f32_e32 v37, v25, v211
	v_mul_f32_e32 v56, v22, v208
	v_mul_f32_e32 v57, v23, v209
	v_mul_f32_e32 v58, v20, v214
	v_mul_f32_e32 v59, v21, v215
	v_mul_f32_e32 v60, v18, v212
	v_mul_f32_e32 v61, v19, v213
	v_mul_f32_e32 v40, v32, v210
	v_mul_f32_e32 v41, v33, v211
	v_mul_f32_e32 v38, v30, v208
	v_mul_f32_e32 v39, v31, v209
	v_mul_f32_e32 v44, v28, v214
	v_mul_f32_e32 v45, v29, v215
	v_mul_f32_e32 v42, v26, v212
	v_mul_f32_e32 v43, v27, v213
	v_fma_f32 v32, v32, v218, -v36
	v_fma_f32 v33, v33, v219, -v37
	v_fma_f32 v30, v30, v216, -v56
	v_fma_f32 v31, v31, v217, -v57
	v_fma_f32 v28, v28, v222, -v58
	v_fma_f32 v29, v29, v223, -v59
	v_fma_f32 v26, v26, v220, -v60
	v_fma_f32 v27, v27, v221, -v61
	v_fma_f32 v24, v24, v218, v40
	v_fma_f32 v25, v25, v219, v41
	v_fma_f32 v22, v22, v216, v38
	v_fma_f32 v23, v23, v217, v39
	v_fma_f32 v20, v20, v222, v44
	v_fma_f32 v21, v21, v223, v45
	v_fma_f32 v18, v18, v220, v42
	v_fma_f32 v19, v19, v221, v43
	v_cvt_pk_bf16_f32 v36, v30, v31
	v_cvt_pk_bf16_f32 v37, v32, v33
	v_cvt_pk_bf16_f32 v38, v26, v27
	v_cvt_pk_bf16_f32 v39, v28, v29
	v_cvt_pk_bf16_f32 v40, v22, v23
	v_cvt_pk_bf16_f32 v41, v24, v25
	s_nop 0
	v_cvt_pk_bf16_f32 v42, v18, v19
	v_cvt_pk_bf16_f32 v43, v20, v21
	global_store_dwordx4 v[54:55], v[36:39], off
	global_store_dwordx4 v[54:55], v[40:43], off offset:64
	s_and_saveexec_b64 s[0:1], vcc
	s_cbranch_execz .LBB0_358
	v_lshl_add_u64 v[34:35], s[16:17], 2, v[34:35]
	v_lshlrev_b32_e32 v36, 2, v138
	v_mov_b32_e32 v37, v1
	v_lshl_add_u64 v[34:35], v[34:35], 0, v[36:37]
	global_store_dwordx4 v[34:35], v[30:33], off offset:-4096
	global_store_dwordx4 v[34:35], v[26:29], off offset:-4080
	global_store_dwordx4 v[34:35], v[22:25], off offset:-3968
	global_store_dwordx4 v[34:35], v[18:21], off offset:-3952

.LBB0_371:
	s_and_b64 vcc, exec, s[4:5]
	s_cbranch_vccz .LBB0_241
	v_and_b32_e32 v0, 0x7ff, v26
	v_cmp_gt_i32_e32 vcc, s94, v26
	v_lshl_add_u64 v[20:21], s[16:17], 1, v[20:21]
	v_mov_b32_e32 v159, v1
	v_cndmask_b32_e32 v0, v169, v0, vcc
	v_lshlrev_b32_e32 v0, 7, v0
	v_lshl_add_u64 v[26:27], v[142:143], 0, v[0:1]
	s_nop 0
	v_lshl_add_u64 v[34:35], v[140:141], 0, v[0:1]
	s_nop 0
	v_lshl_add_u64 v[38:39], v[20:21], 0, v[158:159]
	v_cmp_ne_u64_e32 vcc, 0, v[18:19]
	s_waitcnt vmcnt(2)
	v_mul_f32_e32 v20, v8, v226
	v_mul_f32_e32 v21, v9, v227
	v_mul_f32_e32 v40, v6, v224
	v_mul_f32_e32 v41, v7, v225
	v_mul_f32_e32 v42, v4, v230
	v_mul_f32_e32 v43, v5, v231
	v_mul_f32_e32 v44, v2, v228
	v_mul_f32_e32 v45, v3, v229
	v_mul_f32_e32 v24, v16, v226
	v_mul_f32_e32 v25, v17, v227
	v_mul_f32_e32 v22, v14, v224
	v_mul_f32_e32 v23, v15, v225
	v_mul_f32_e32 v28, v12, v230
	v_mul_f32_e32 v29, v13, v231
	v_mul_f32_e32 v26, v10, v228
	v_mul_f32_e32 v27, v11, v229
	v_fma_f32 v16, v16, v234, -v20
	v_fma_f32 v17, v17, v235, -v21
	v_fma_f32 v14, v14, v232, -v40
	v_fma_f32 v15, v15, v233, -v41
	v_fma_f32 v12, v12, v238, -v42
	v_fma_f32 v13, v13, v239, -v43
	v_fma_f32 v10, v10, v236, -v44
	v_fma_f32 v11, v11, v237, -v45
	v_fma_f32 v8, v8, v234, v24
	v_fma_f32 v9, v9, v235, v25
	v_fma_f32 v6, v6, v232, v22
	v_fma_f32 v7, v7, v233, v23
	v_fma_f32 v4, v4, v238, v28
	v_fma_f32 v5, v5, v239, v29
	v_fma_f32 v2, v2, v236, v26
	v_fma_f32 v3, v3, v237, v27
	v_cvt_pk_bf16_f32 v20, v14, v15
	v_cvt_pk_bf16_f32 v21, v16, v17
	v_cvt_pk_bf16_f32 v22, v10, v11
	v_cvt_pk_bf16_f32 v23, v12, v13
	v_cvt_pk_bf16_f32 v24, v6, v7
	v_cvt_pk_bf16_f32 v25, v8, v9
	s_nop 0
	v_cvt_pk_bf16_f32 v26, v2, v3
	v_cvt_pk_bf16_f32 v27, v4, v5
	global_store_dwordx4 v[38:39], v[20:23], off
	global_store_dwordx4 v[38:39], v[24:27], off offset:64
	s_and_saveexec_b64 s[0:1], vcc
	s_cbranch_execz .LBB0_240
	v_lshl_add_u64 v[18:19], s[16:17], 2, v[18:19]
	v_lshlrev_b32_e32 v0, 2, v138
	v_lshl_add_u64 v[18:19], v[18:19], 0, v[0:1]
	global_store_dwordx4 v[18:19], v[14:17], off offset:-4096
	global_store_dwordx4 v[18:19], v[10:13], off offset:-4080
	global_store_dwordx4 v[18:19], v[6:9], off offset:-3968
	global_store_dwordx4 v[18:19], v[2:5], off offset:-3952
	s_branch .LBB0_240

.LBB0_599:
	v_ashrrev_i32_e32 v9, 31, v2
	v_mov_b32_e32 v8, v2
	v_ashrrev_i32_e32 v7, 31, v3
	v_mov_b32_e32 v6, v3
	v_lshl_add_u64 v[8:9], v[8:9], 2, s[48:49]
	v_lshl_add_u64 v[6:7], v[6:7], 2, s[48:49]
	global_load_dword v8, v[8:9], off
	s_nop 0
	global_load_dword v9, v[6:7], off
	v_add_u32_e32 v0, -2, v0
	v_add_u32_e32 v5, 0xfffff800, v4
	v_cmp_eq_u32_e32 vcc, 0, v0
	v_add_u32_e32 v3, 0x400, v3
	v_add_u32_e32 v2, 0x400, v2
	s_or_b64 s[56:57], vcc, s[56:57]
	s_waitcnt vmcnt(0)
	v_mul_f32_e64 v6, v8, s68
	v_mul_f32_e64 v7, v9, s68
	ds_write_b32 v5, v6
	ds_write_b32 v4, v7
	v_add_u32_e32 v4, 0x1000, v4
	s_andn2_b64 exec, exec, s[56:57]
	s_cbranch_execnz .LBB0_599
	s_or_b64 exec, exec, s[56:57]
	s_mov_b64 s[56:57], 0
	s_mov_b64 s[58:59], exec
	v_readlane_b32 s2, v250, 37
	v_readlane_b32 s3, v250, 38
	s_and_b64 s[2:3], s[58:59], s[2:3]
	s_mov_b64 exec, s[2:3]
	s_mov_b64 s[56:57], exec
	v_lshlrev_b32_e32 v0, 2, v215
	s_or_b64 exec, exec, s[58:59]
	s_orn2_b64 s[56:57], s[56:57], exec
	v_mov_b32_e32 v2, v215

.LBB0_657:
	s_andn2_b64 vcc, exec, s[0:1]
	s_mov_b64 s[16:17], -1
	s_cbranch_vccnz .LBB0_668
	s_add_i32 s51, s13, s23
	s_sub_i32 s0, s51, 64
	s_cmp_ge_i32 s0, s53
	s_mov_b64 s[16:17], 0
	s_cbranch_scc1 .LBB0_668
	v_add3_u32 v0, s28, v209, v210
	ds_read_b128 v[2:5], v0
	s_sub_i32 s0, s51, 63
	s_cmp_lt_i32 s0, s20
	s_cselect_b64 s[62:63], -1, 0
	s_cmp_ge_i32 s0, s20
	v_mov_b32_e32 v15, 0
	s_waitcnt lgkmcnt(0)
	v_mfma_f32_32x32x16_bf16 v[48:63], v[2:5], v[96:99], 0
	ds_read_b128 v[2:5], v0 offset:4608
	s_waitcnt lgkmcnt(0)
	v_mfma_f32_32x32x16_bf16 v[64:79], v[2:5], v[96:99], 0
	ds_read_b128 v[2:5], v0 offset:32
	s_waitcnt lgkmcnt(0)
	v_mfma_f32_32x32x16_bf16 v[48:63], v[2:5], v[100:103], v[48:63]
	ds_read_b128 v[2:5], v0 offset:4640
	s_waitcnt lgkmcnt(0)
	v_mfma_f32_32x32x16_bf16 v[64:79], v[2:5], v[100:103], v[64:79]
	ds_read_b128 v[2:5], v0 offset:64
	s_waitcnt lgkmcnt(0)
	v_mfma_f32_32x32x16_bf16 v[48:63], v[2:5], v[104:107], v[48:63]
	ds_read_b128 v[2:5], v0 offset:4672
	s_waitcnt lgkmcnt(0)
	v_mfma_f32_32x32x16_bf16 v[64:79], v[2:5], v[104:107], v[64:79]
	ds_read_b128 v[2:5], v0 offset:96
	s_waitcnt lgkmcnt(0)
	v_mfma_f32_32x32x16_bf16 v[48:63], v[2:5], v[108:111], v[48:63]
	ds_read_b128 v[2:5], v0 offset:4704
	s_waitcnt lgkmcnt(0)
	v_mfma_f32_32x32x16_bf16 v[64:79], v[2:5], v[108:111], v[64:79]
	s_cbranch_scc1 .LBB0_663
	s_nop 10
	v_mul_f32_e32 v0, 0x3fb8aa3b, v64
	v_min_f32_e32 v0, 0x42a00000, v0
	v_exp_f32_e32 v2, v0
	v_mul_f32_e32 v0, 0x3fb8aa3b, v65
	v_min_f32_e32 v0, 0x42a00000, v0
	v_exp_f32_e32 v3, v0
	v_add_f32_e32 v0, 1.0, v2
	v_rcp_f32_e32 v6, v0
	v_mul_f32_e32 v5, 0x3fb8aa3b, v67
	v_add_f32_e32 v0, 1.0, v3
	v_mul_f32_e32 v10, 0x3fb8aa3b, v69
	v_rcp_f32_e32 v7, v0
	v_mul_f32_e32 v0, 0x3fb8aa3b, v66
	v_min_f32_e32 v5, 0x42a00000, v5
	v_min_f32_e32 v10, 0x42a00000, v10
	v_min_f32_e32 v0, 0x42a00000, v0
	v_exp_f32_e32 v8, v5
	v_mul_f32_e32 v5, 0x3fb8aa3b, v68
	v_exp_f32_e32 v12, v10
	v_mul_f32_e32 v10, 0x3fb8aa3b, v70
	v_exp_f32_e32 v0, v0
	v_min_f32_e32 v5, 0x42a00000, v5
	v_min_f32_e32 v10, 0x42a00000, v10
	v_exp_f32_e32 v9, v5
	v_exp_f32_e32 v13, v10
	v_add_f32_e32 v4, 1.0, v0
	v_add_f32_e32 v10, 1.0, v12
	v_rcp_f32_e32 v180, v4
	v_add_f32_e32 v4, 1.0, v8
	v_add_f32_e32 v5, 1.0, v9
	v_rcp_f32_e32 v66, v10
	v_add_f32_e32 v10, 1.0, v13
	v_rcp_f32_e32 v4, v4
	v_rcp_f32_e32 v5, v5
	v_rcp_f32_e32 v67, v10
	v_mul_f32_e32 v10, 0x3fb8aa3b, v71
	v_min_f32_e32 v10, 0x42a00000, v10
	v_exp_f32_e32 v65, v10
	v_mul_f32_e32 v10, v8, v4
	v_mul_f32_e32 v11, v9, v5
	v_mul_f32_e32 v8, v12, v66
	v_mul_f32_e32 v9, v13, v67
	v_mul_f32_e32 v13, 0x3fb8aa3b, v72
	v_min_f32_e32 v13, 0x42a00000, v13
	v_exp_f32_e32 v14, v13
	v_mul_f32_e32 v13, 0x3fb8aa3b, v73
	v_min_f32_e32 v13, 0x42a00000, v13
	v_exp_f32_e32 v15, v13
	v_add_f32_e32 v12, 1.0, v65
	v_rcp_f32_e32 v13, v12
	v_add_f32_e32 v12, 1.0, v14
	v_rcp_f32_e32 v64, v12
	v_add_f32_e32 v12, 1.0, v15
	v_rcp_f32_e32 v68, v12
	v_mul_f32_e32 v12, 0x3fb8aa3b, v74
	v_min_f32_e32 v12, 0x42a00000, v12
	v_exp_f32_e32 v12, v12
	v_mul_f32_e32 v181, v65, v13
	v_mov_b32_e32 v65, v68
	v_mul_f32_e32 v14, v14, v64
	v_mul_f32_e32 v15, v15, v65
	v_add_f32_e32 v65, 1.0, v12
	v_rcp_f32_e32 v70, v65
	v_mul_f32_e32 v65, 0x3fb8aa3b, v75
	v_min_f32_e32 v65, 0x42a00000, v65
	v_exp_f32_e32 v72, v65
	v_mul_f32_e32 v65, 0x3fb8aa3b, v76
	v_min_f32_e32 v65, 0x42a00000, v65
	v_exp_f32_e32 v73, v65
	v_mul_f32_e32 v182, v12, v70
	v_add_f32_e32 v12, 1.0, v72
	v_rcp_f32_e32 v74, v12
	v_add_f32_e32 v12, 1.0, v73
	v_rcp_f32_e32 v65, v12
	v_mul_f32_e32 v12, 0x3fb8aa3b, v77
	v_min_f32_e32 v12, 0x42a00000, v12
	v_exp_f32_e32 v76, v12
	v_mul_f32_e32 v12, 0x3fb8aa3b, v78
	v_min_f32_e32 v12, 0x42a00000, v12
	v_exp_f32_e32 v77, v12
	v_add_f32_e32 v12, 1.0, v76
	v_rcp_f32_e32 v69, v12
	v_mov_b32_e32 v75, v65
	v_add_f32_e32 v12, 1.0, v77
	v_rcp_f32_e32 v71, v12
	v_mul_f32_e32 v12, 0x3fb8aa3b, v79
	v_min_f32_e32 v12, 0x42a00000, v12
	v_exp_f32_e32 v12, v12
	v_mul_f32_e32 v78, v72, v74
	v_mul_f32_e32 v79, v73, v75
	v_mov_b32_e32 v72, v69
	v_mov_b32_e32 v73, v71
	v_add_f32_e32 v75, 1.0, v12
	v_rcp_f32_e32 v75, v75
	s_add_i32 s0, s51, -1
	v_mul_f32_e32 v2, v2, v6
	v_mul_f32_e32 v3, v3, v7
	v_mul_f32_e32 v0, v0, v180
	v_mul_f32_e32 v76, v76, v72
	v_mul_f32_e32 v77, v77, v73
	s_cmp_lt_i32 s0, s20
	v_mul_f32_e32 v183, v12, v75
	s_cbranch_scc1 .LBB0_662
	v_add3_u32 v12, s21, v151, 64
	v_cmp_lt_i32_e32 vcc, 0, v12
	v_cmp_lt_i32_e64 s[0:1], 1, v12
	v_cmp_lt_i32_e64 s[18:19], 24, v12
	v_cndmask_b32_e32 v6, 1.0, v6, vcc
	v_cndmask_b32_e32 v2, 0, v2, vcc
	v_cmp_lt_i32_e32 vcc, 2, v12
	v_cndmask_b32_e64 v7, 1.0, v7, s[0:1]
	v_cndmask_b32_e64 v3, 0, v3, s[0:1]
	v_cndmask_b32_e32 v180, 1.0, v180, vcc
	v_cndmask_b32_e32 v0, 0, v0, vcc
	v_cmp_lt_i32_e32 vcc, 3, v12
	v_cmp_lt_i32_e64 s[0:1], 8, v12
	v_cmp_lt_i32_e64 s[16:17], 18, v12
	v_cndmask_b32_e32 v4, 1.0, v4, vcc
	v_cndmask_b32_e32 v10, 0, v10, vcc
	v_cmp_lt_i32_e32 vcc, 9, v12
	v_cndmask_b32_e64 v5, 1.0, v5, s[0:1]
	v_cndmask_b32_e64 v11, 0, v11, s[0:1]
	v_cndmask_b32_e32 v66, 1.0, v66, vcc
	v_cndmask_b32_e32 v8, 0, v8, vcc
	v_cmp_lt_i32_e32 vcc, 11, v12
	v_cmp_lt_i32_e64 s[0:1], 10, v12
	v_cndmask_b32_e64 v65, 1.0, v65, s[18:19]
	v_cndmask_b32_e32 v13, 1.0, v13, vcc
	v_cndmask_b32_e32 v181, 0, v181, vcc
	v_cmp_lt_i32_e32 vcc, 17, v12
	v_cndmask_b32_e64 v67, 1.0, v67, s[0:1]
	v_cndmask_b32_e64 v9, 0, v9, s[0:1]
	v_cndmask_b32_e32 v15, 0, v15, vcc
	v_cmp_lt_i32_e64 s[0:1], 16, v12
	v_cndmask_b32_e32 v68, 1.0, v68, vcc
	v_cmp_lt_i32_e32 vcc, 26, v12
	v_cndmask_b32_e64 v14, 0, v14, s[0:1]
	v_cndmask_b32_e64 v64, 1.0, v64, s[0:1]
	v_cndmask_b32_e64 v79, 0, v79, s[18:19]
	v_cmp_lt_i32_e64 s[0:1], 19, v12
	v_cmp_lt_i32_e64 s[18:19], 25, v12
	v_cndmask_b32_e32 v71, 1.0, v71, vcc
	v_cndmask_b32_e32 v77, 0, v77, vcc
	v_cmp_lt_i32_e32 vcc, 27, v12
	v_cndmask_b32_e64 v182, 0, v182, s[16:17]
	v_cndmask_b32_e64 v78, 0, v78, s[0:1]
	v_cndmask_b32_e64 v69, 1.0, v69, s[18:19]
	v_cndmask_b32_e64 v70, 1.0, v70, s[16:17]
	v_cndmask_b32_e64 v76, 0, v76, s[18:19]
	v_cndmask_b32_e32 v75, 1.0, v75, vcc
	v_cndmask_b32_e64 v74, 1.0, v74, s[0:1]
	v_cndmask_b32_e32 v183, 0, v183, vcc
.LBB0_662:
	v_mul_f32_e32 v12, v67, v13
	v_and_b32_e32 v72, 64, v199
	v_mul_f32_e32 v67, v66, v12
	v_xor_b32_e32 v66, 32, v199
	v_add_u32_e32 v72, 64, v72
	v_mul_f32_e32 v73, v180, v4
	v_cmp_lt_i32_e32 vcc, v66, v72
	v_mul_f32_e32 v72, v7, v73
	v_mul_f32_e32 v224, v6, v72
	v_mul_f32_e32 v6, v70, v74
	v_mul_f32_e32 v7, v71, v75
	v_cndmask_b32_e32 v66, v199, v66, vcc
	v_mul_f32_e32 v184, v68, v6
	v_mul_f32_e32 v185, v69, v7
	v_mul_f32_e32 v5, v5, v67
	v_lshlrev_b32_e32 v187, 2, v66
	v_mul_f32_e32 v64, v64, v184
	v_mul_f32_e32 v65, v65, v185
	ds_bpermute_b32 v188, v187, v5
	ds_bpermute_b32 v225, v187, v224
	ds_bpermute_b32 v186, v187, v64
	ds_bpermute_b32 v187, v187, v65
	v_mov_b32_e32 v190, v184
	s_waitcnt lgkmcnt(3)
	v_mul_f32_e32 v176, v5, v188
	v_cndmask_b32_e64 v69, 1.0, v188, s[6:7]
	v_mov_b32_e32 v68, v177
	s_waitcnt lgkmcnt(0)
	v_mul_f32_e32 v64, v64, v186
	v_mul_f32_e32 v65, v65, v187
	v_cndmask_b32_e64 v66, 1.0, v225, s[6:7]
	v_mul_f32_e32 v184, v177, v65
	v_pk_mul_f32 v[64:65], v[64:65], v[64:65] op_sel:[0,1] op_sel_hi:[0,1]
	v_mul_f32_e32 v192, v176, v64
	v_mul_f32_e32 v193, v177, v65
	v_cndmask_b32_e64 v188, 1.0, v186, s[6:7]
	v_mul_f32_e32 v64, v68, v192
	v_mul_f32_e32 v65, v69, v193
	v_mov_b32_e32 v191, v6
	v_mul_f32_e32 v66, v66, v64
	v_mul_f32_e32 v67, v67, v65
	v_mul_f32_e32 v176, v181, v65
	v_mul_f32_e32 v68, v72, v66
	v_mul_f32_e32 v69, v73, v66
	v_mul_f32_e32 v70, v10, v66
	v_mul_f32_e32 v71, v11, v67
	v_mul_f32_e32 v72, v2, v68
	v_mul_f32_e32 v73, v3, v69
	v_mul_f32_e32 v2, v4, v66
	v_mul_f32_e32 v180, v0, v2
	v_cndmask_b32_e64 v0, 1.0, v187, s[6:7]
	v_mul_f32_e32 v2, v12, v65
	v_mul_f32_e32 v3, v13, v65
	v_mul_f32_e32 v189, v177, v0
	v_mul_f32_e32 v68, v8, v2
	v_mul_f32_e32 v69, v9, v3
	v_mul_f32_e32 v2, v188, v184
	v_mul_f32_e32 v3, v189, v185
	s_nop 0
	v_mul_f32_e32 v4, v190, v2
	v_mul_f32_e32 v5, v191, v2
	v_mul_f32_e32 v0, v74, v2
	v_mul_f32_e32 v64, v78, v2
	v_mul_f32_e32 v65, v79, v3
	v_mov_b32_e32 v74, v7
	v_mov_b32_e32 v2, v189
	v_mul_f32_e32 v3, v75, v2
	v_mul_f32_e32 v2, v74, v2
	v_mul_f32_e32 v66, v14, v4
	v_mul_f32_e32 v67, v15, v5
	v_mul_f32_e32 v14, v76, v2
	v_mul_f32_e32 v15, v77, v3
	v_mul_f32_e32 v2, v224, v225
	v_mul_f32_e32 v2, v2, v192
	v_mul_f32_e32 v0, v182, v0
	v_mul_f32_e32 v74, v183, v189
	v_mul_f32_e32 v177, v177, v2
	s_branch .LBB0_664

.LBB0_668:
	s_cmp_gt_i32 s25, s8
	s_cselect_b64 s[0:1], -1, 0
	s_and_b64 s[0:1], s[0:1], s[42:43]
	s_andn2_b64 vcc, exec, s[0:1]
	s_cbranch_vccnz .LBB0_675
	s_xor_b64 s[0:1], s[16:17], -1
	s_andn2_b64 vcc, exec, s[0:1]
	s_mov_b64 s[16:17], -1
	s_cbranch_vccnz .LBB0_675
	s_add_i32 s25, s13, s23
	s_add_i32 s0, s25, 0xffffff80
	s_cmp_ge_i32 s0, s53
	s_mov_b64 s[16:17], 0
	s_cbranch_scc1 .LBB0_675
	v_add3_u32 v0, s26, v209, v210
	ds_read_b128 v[2:5], v0
	s_add_i32 s0, s25, 0xffffff81
	s_cmp_lt_i32 s0, s20
	s_cselect_b64 s[62:63], -1, 0
	s_cmp_ge_i32 s0, s20
	v_mov_b32_e32 v15, 0
	s_waitcnt lgkmcnt(0)
	v_mfma_f32_32x32x16_bf16 v[48:63], v[2:5], v[96:99], 0
	ds_read_b128 v[2:5], v0 offset:4608
	s_waitcnt lgkmcnt(0)
	v_mfma_f32_32x32x16_bf16 v[64:79], v[2:5], v[96:99], 0
	ds_read_b128 v[2:5], v0 offset:32
	s_waitcnt lgkmcnt(0)
	v_mfma_f32_32x32x16_bf16 v[48:63], v[2:5], v[100:103], v[48:63]
	ds_read_b128 v[2:5], v0 offset:4640
	s_waitcnt lgkmcnt(0)
	v_mfma_f32_32x32x16_bf16 v[64:79], v[2:5], v[100:103], v[64:79]
	ds_read_b128 v[2:5], v0 offset:64
	s_waitcnt lgkmcnt(0)
	v_mfma_f32_32x32x16_bf16 v[48:63], v[2:5], v[104:107], v[48:63]
	ds_read_b128 v[2:5], v0 offset:4672
	s_waitcnt lgkmcnt(0)
	v_mfma_f32_32x32x16_bf16 v[64:79], v[2:5], v[104:107], v[64:79]
	ds_read_b128 v[2:5], v0 offset:96
	s_waitcnt lgkmcnt(0)
	v_mfma_f32_32x32x16_bf16 v[48:63], v[2:5], v[108:111], v[48:63]
	ds_read_b128 v[2:5], v0 offset:4704
	s_waitcnt lgkmcnt(0)
	v_mfma_f32_32x32x16_bf16 v[64:79], v[2:5], v[108:111], v[64:79]
	s_cbranch_scc1 .LBB0_677
	s_nop 10
	v_mul_f32_e32 v0, 0x3fb8aa3b, v64
	v_min_f32_e32 v0, 0x42a00000, v0
	v_exp_f32_e32 v2, v0
	v_mul_f32_e32 v0, 0x3fb8aa3b, v65
	v_min_f32_e32 v0, 0x42a00000, v0
	v_exp_f32_e32 v3, v0
	v_add_f32_e32 v0, 1.0, v2
	v_rcp_f32_e32 v6, v0
	v_mul_f32_e32 v5, 0x3fb8aa3b, v67
	v_add_f32_e32 v0, 1.0, v3
	v_mul_f32_e32 v10, 0x3fb8aa3b, v69
	v_rcp_f32_e32 v7, v0
	v_mul_f32_e32 v0, 0x3fb8aa3b, v66
	v_min_f32_e32 v5, 0x42a00000, v5
	v_min_f32_e32 v10, 0x42a00000, v10
	v_min_f32_e32 v0, 0x42a00000, v0
	v_exp_f32_e32 v8, v5
	v_mul_f32_e32 v5, 0x3fb8aa3b, v68
	v_exp_f32_e32 v12, v10
	v_mul_f32_e32 v10, 0x3fb8aa3b, v70
	v_exp_f32_e32 v0, v0
	v_min_f32_e32 v5, 0x42a00000, v5
	v_min_f32_e32 v10, 0x42a00000, v10
	v_exp_f32_e32 v9, v5
	v_exp_f32_e32 v13, v10
	v_add_f32_e32 v4, 1.0, v0
	v_add_f32_e32 v10, 1.0, v12
	v_rcp_f32_e32 v180, v4
	v_add_f32_e32 v4, 1.0, v8
	v_add_f32_e32 v5, 1.0, v9
	v_rcp_f32_e32 v66, v10
	v_add_f32_e32 v10, 1.0, v13
	v_rcp_f32_e32 v4, v4
	v_rcp_f32_e32 v5, v5
	v_rcp_f32_e32 v67, v10
	v_mul_f32_e32 v10, 0x3fb8aa3b, v71
	v_min_f32_e32 v10, 0x42a00000, v10
	v_exp_f32_e32 v65, v10
	v_mul_f32_e32 v10, v8, v4
	v_mul_f32_e32 v11, v9, v5
	v_mul_f32_e32 v8, v12, v66
	v_mul_f32_e32 v9, v13, v67
	v_mul_f32_e32 v13, 0x3fb8aa3b, v72
	v_min_f32_e32 v13, 0x42a00000, v13
	v_exp_f32_e32 v14, v13
	v_mul_f32_e32 v13, 0x3fb8aa3b, v73
	v_min_f32_e32 v13, 0x42a00000, v13
	v_exp_f32_e32 v15, v13
	v_add_f32_e32 v12, 1.0, v65
	v_rcp_f32_e32 v13, v12
	v_add_f32_e32 v12, 1.0, v14
	v_rcp_f32_e32 v64, v12
	v_add_f32_e32 v12, 1.0, v15
	v_rcp_f32_e32 v68, v12
	v_mul_f32_e32 v12, 0x3fb8aa3b, v74
	v_min_f32_e32 v12, 0x42a00000, v12
	v_exp_f32_e32 v12, v12
	v_mul_f32_e32 v181, v65, v13
	v_mov_b32_e32 v65, v68
	v_mul_f32_e32 v14, v14, v64
	v_mul_f32_e32 v15, v15, v65
	v_add_f32_e32 v65, 1.0, v12
	v_rcp_f32_e32 v70, v65
	v_mul_f32_e32 v65, 0x3fb8aa3b, v75
	v_min_f32_e32 v65, 0x42a00000, v65
	v_exp_f32_e32 v72, v65
	v_mul_f32_e32 v65, 0x3fb8aa3b, v76
	v_min_f32_e32 v65, 0x42a00000, v65
	v_exp_f32_e32 v73, v65
	v_mul_f32_e32 v182, v12, v70
	v_add_f32_e32 v12, 1.0, v72
	v_rcp_f32_e32 v74, v12
	v_add_f32_e32 v12, 1.0, v73
	v_rcp_f32_e32 v65, v12
	v_mul_f32_e32 v12, 0x3fb8aa3b, v77
	v_min_f32_e32 v12, 0x42a00000, v12
	v_exp_f32_e32 v76, v12
	v_mul_f32_e32 v12, 0x3fb8aa3b, v78
	v_min_f32_e32 v12, 0x42a00000, v12
	v_exp_f32_e32 v77, v12
	v_add_f32_e32 v12, 1.0, v76
	v_rcp_f32_e32 v69, v12
	v_mov_b32_e32 v75, v65
	v_add_f32_e32 v12, 1.0, v77
	v_rcp_f32_e32 v71, v12
	v_mul_f32_e32 v12, 0x3fb8aa3b, v79
	v_min_f32_e32 v12, 0x42a00000, v12
	v_exp_f32_e32 v12, v12
	v_mul_f32_e32 v78, v72, v74
	v_mul_f32_e32 v79, v73, v75
	v_mov_b32_e32 v72, v69
	v_mov_b32_e32 v73, v71
	v_add_f32_e32 v75, 1.0, v12
	v_rcp_f32_e32 v75, v75
	s_add_i32 s0, s25, 0xffffffbf
	v_mul_f32_e32 v2, v2, v6
	v_mul_f32_e32 v3, v3, v7
	v_mul_f32_e32 v0, v0, v180
	v_mul_f32_e32 v76, v76, v72
	v_mul_f32_e32 v77, v77, v73
	s_cmp_lt_i32 s0, s20
	v_mul_f32_e32 v183, v12, v75
	s_cbranch_scc1 .LBB0_674
	v_add_u32_e32 v12, s21, v151
	v_add_u32_e32 v12, 0x80, v12
	v_cmp_lt_i32_e32 vcc, 0, v12
	v_cmp_lt_i32_e64 s[0:1], 1, v12
	v_cmp_lt_i32_e64 s[18:19], 24, v12
	v_cndmask_b32_e32 v6, 1.0, v6, vcc
	v_cndmask_b32_e32 v2, 0, v2, vcc
	v_cmp_lt_i32_e32 vcc, 2, v12
	v_cndmask_b32_e64 v7, 1.0, v7, s[0:1]
	v_cndmask_b32_e64 v3, 0, v3, s[0:1]
	v_cndmask_b32_e32 v180, 1.0, v180, vcc
	v_cndmask_b32_e32 v0, 0, v0, vcc
	v_cmp_lt_i32_e32 vcc, 3, v12
	v_cmp_lt_i32_e64 s[0:1], 8, v12
	v_cmp_lt_i32_e64 s[16:17], 18, v12
	v_cndmask_b32_e32 v4, 1.0, v4, vcc
	v_cndmask_b32_e32 v10, 0, v10, vcc
	v_cmp_lt_i32_e32 vcc, 9, v12
	v_cndmask_b32_e64 v5, 1.0, v5, s[0:1]
	v_cndmask_b32_e64 v11, 0, v11, s[0:1]
	v_cndmask_b32_e32 v66, 1.0, v66, vcc
	v_cndmask_b32_e32 v8, 0, v8, vcc
	v_cmp_lt_i32_e32 vcc, 11, v12
	v_cmp_lt_i32_e64 s[0:1], 10, v12
	v_cndmask_b32_e64 v65, 1.0, v65, s[18:19]
	v_cndmask_b32_e32 v13, 1.0, v13, vcc
	v_cndmask_b32_e32 v181, 0, v181, vcc
	v_cmp_lt_i32_e32 vcc, 17, v12
	v_cndmask_b32_e64 v67, 1.0, v67, s[0:1]
	v_cndmask_b32_e64 v9, 0, v9, s[0:1]
	v_cndmask_b32_e32 v15, 0, v15, vcc
	v_cmp_lt_i32_e64 s[0:1], 16, v12
	v_cndmask_b32_e32 v68, 1.0, v68, vcc
	v_cmp_lt_i32_e32 vcc, 26, v12
	v_cndmask_b32_e64 v14, 0, v14, s[0:1]
	v_cndmask_b32_e64 v64, 1.0, v64, s[0:1]
	v_cndmask_b32_e64 v79, 0, v79, s[18:19]
	v_cmp_lt_i32_e64 s[0:1], 19, v12
	v_cmp_lt_i32_e64 s[18:19], 25, v12
	v_cndmask_b32_e32 v71, 1.0, v71, vcc
	v_cndmask_b32_e32 v77, 0, v77, vcc
	v_cmp_lt_i32_e32 vcc, 27, v12
	v_cndmask_b32_e64 v182, 0, v182, s[16:17]
	v_cndmask_b32_e64 v78, 0, v78, s[0:1]
	v_cndmask_b32_e64 v69, 1.0, v69, s[18:19]
	v_cndmask_b32_e64 v70, 1.0, v70, s[16:17]
	v_cndmask_b32_e64 v76, 0, v76, s[18:19]
	v_cndmask_b32_e32 v75, 1.0, v75, vcc
	v_cndmask_b32_e64 v74, 1.0, v74, s[0:1]
	v_cndmask_b32_e32 v183, 0, v183, vcc
.LBB0_674:
	v_mul_f32_e32 v12, v67, v13
	v_and_b32_e32 v72, 64, v199
	v_mul_f32_e32 v67, v66, v12
	v_xor_b32_e32 v66, 32, v199
	v_add_u32_e32 v72, 64, v72
	v_mul_f32_e32 v73, v180, v4
	v_cmp_lt_i32_e32 vcc, v66, v72
	v_mul_f32_e32 v72, v7, v73
	v_mul_f32_e32 v224, v6, v72
	v_mul_f32_e32 v6, v70, v74
	v_mul_f32_e32 v7, v71, v75
	v_cndmask_b32_e32 v66, v199, v66, vcc
	v_mul_f32_e32 v184, v68, v6
	v_mul_f32_e32 v185, v69, v7
	v_mul_f32_e32 v5, v5, v67
	v_lshlrev_b32_e32 v187, 2, v66
	v_mul_f32_e32 v64, v64, v184
	v_mul_f32_e32 v65, v65, v185
	ds_bpermute_b32 v188, v187, v5
	ds_bpermute_b32 v225, v187, v224
	ds_bpermute_b32 v186, v187, v64
	ds_bpermute_b32 v187, v187, v65
	v_mov_b32_e32 v190, v184
	s_waitcnt lgkmcnt(3)
	v_mul_f32_e32 v176, v5, v188
	v_cndmask_b32_e64 v69, 1.0, v188, s[6:7]
	v_mov_b32_e32 v68, v177
	s_waitcnt lgkmcnt(0)
	v_mul_f32_e32 v64, v64, v186
	v_mul_f32_e32 v65, v65, v187
	v_cndmask_b32_e64 v66, 1.0, v225, s[6:7]
	v_mul_f32_e32 v184, v177, v65
	v_pk_mul_f32 v[64:65], v[64:65], v[64:65] op_sel:[0,1] op_sel_hi:[0,1]
	v_mul_f32_e32 v192, v176, v64
	v_mul_f32_e32 v193, v177, v65
	v_cndmask_b32_e64 v188, 1.0, v186, s[6:7]
	v_mul_f32_e32 v64, v68, v192
	v_mul_f32_e32 v65, v69, v193
	v_mov_b32_e32 v191, v6
	v_mul_f32_e32 v66, v66, v64
	v_mul_f32_e32 v67, v67, v65
	v_mul_f32_e32 v176, v181, v65
	v_mul_f32_e32 v68, v72, v66
	v_mul_f32_e32 v69, v73, v66
	v_mul_f32_e32 v70, v10, v66
	v_mul_f32_e32 v71, v11, v67
	v_mul_f32_e32 v72, v2, v68
	v_mul_f32_e32 v73, v3, v69
	v_mul_f32_e32 v2, v4, v66
	v_mul_f32_e32 v180, v0, v2
	v_cndmask_b32_e64 v0, 1.0, v187, s[6:7]
	v_mul_f32_e32 v2, v12, v65
	v_mul_f32_e32 v3, v13, v65
	v_mul_f32_e32 v189, v177, v0
	v_mul_f32_e32 v68, v8, v2
	v_mul_f32_e32 v69, v9, v3
	v_mul_f32_e32 v2, v188, v184
	v_mul_f32_e32 v3, v189, v185
	s_mov_b64 s[26:27], 0x800
	v_mul_f32_e32 v4, v190, v2
	v_mul_f32_e32 v5, v191, v2
	v_mul_f32_e32 v0, v74, v2
	v_mul_f32_e32 v64, v78, v2
	v_mul_f32_e32 v65, v79, v3
	v_mov_b32_e32 v74, v7
	v_mov_b32_e32 v2, v189
	v_mul_f32_e32 v3, v75, v2
	v_mul_f32_e32 v2, v74, v2
	v_mul_f32_e32 v66, v14, v4
	v_mul_f32_e32 v67, v15, v5
	v_mul_f32_e32 v14, v76, v2
	v_mul_f32_e32 v15, v77, v3
	v_mul_f32_e32 v2, v224, v225
	v_mul_f32_e32 v2, v2, v192
	v_mul_f32_e32 v0, v182, v0
	v_mul_f32_e32 v74, v183, v189
	v_mul_f32_e32 v177, v177, v2
	s_branch .LBB0_678

.LBB0_718:
	s_ashr_i32 s40, s20, 6
	s_add_i32 s41, s40, -8
	s_and_b64 vcc, exec, s[14:15]
	v_add_u32_e32 v226, s20, v211
	s_cbranch_vccnz .LBB0_735
	s_add_i32 s18, s21, s4
	s_ashr_i32 s19, s18, 6
	s_cmp_le_i32 s19, s40
	s_cselect_b64 s[16:17], -1, 0
	s_cmp_ge_i32 s19, s41
	s_cselect_b64 s[22:23], -1, 0
	s_and_b64 s[16:17], s[16:17], s[22:23]
	s_andn2_b64 vcc, exec, s[16:17]
	s_cbranch_vccnz .LBB0_737
	v_add_u32_e32 v0, v212, v210
	ds_read_b128 v[2:5], v0 offset:4608
	ds_read_b128 v[6:9], v0
	ds_read_b128 v[34:37], v0 offset:32
	ds_read_b128 v[38:41], v0 offset:4640
	ds_read_b128 v[42:45], v0 offset:64
	ds_read_b128 v[46:49], v0 offset:4672
	ds_read_b128 v[50:53], v0 offset:96
	ds_read_b128 v[54:57], v0 offset:4704
	s_waitcnt lgkmcnt(6)
	v_mfma_f32_32x32x16_bf16 v[18:33], v[6:9], v[96:99], 0
	s_add_i32 s19, s18, 0xbf
	s_mov_b64 s[16:17], -1
	s_cmp_gt_i32 s19, s20
	v_mfma_f32_32x32x16_bf16 v[2:17], v[2:5], v[96:99], 0
	s_waitcnt lgkmcnt(5)
	v_mfma_f32_32x32x16_bf16 v[18:33], v[34:37], v[100:103], v[18:33]
	s_waitcnt lgkmcnt(4)
	v_mfma_f32_32x32x16_bf16 v[2:17], v[38:41], v[100:103], v[2:17]
	s_waitcnt lgkmcnt(3)
	v_mfma_f32_32x32x16_bf16 v[18:33], v[42:45], v[104:107], v[18:33]
	s_waitcnt lgkmcnt(2)
	v_mfma_f32_32x32x16_bf16 v[2:17], v[46:49], v[104:107], v[2:17]
	s_waitcnt lgkmcnt(1)
	v_mfma_f32_32x32x16_bf16 v[18:33], v[50:53], v[108:111], v[18:33]
	s_waitcnt lgkmcnt(0)
	v_mfma_f32_32x32x16_bf16 v[2:17], v[54:57], v[108:111], v[2:17]
	s_cbranch_scc1 .LBB0_722
	v_mov_b32_e32 v0, s29
	ds_read_b32 v0, v0
	s_mov_b64 s[16:17], 0
	s_waitcnt lgkmcnt(0)
	s_nop 4
	v_fma_f32 v34, v18, s68, v0
	v_fma_f32 v35, v19, s68, v0
	s_nop 0
	v_fma_f32 v36, v2, s68, v0
	v_fma_f32 v37, v3, s68, v0
	v_fma_f32 v38, v20, s68, v0
	v_fma_f32 v39, v21, s68, v0
	v_fma_f32 v40, v4, s68, v0
	v_fma_f32 v41, v5, s68, v0
	v_fma_f32 v42, v22, s68, v0
	v_fma_f32 v43, v23, s68, v0
	v_fma_f32 v44, v6, s68, v0
	v_fma_f32 v45, v7, s68, v0
	v_fma_f32 v46, v24, s68, v0
	v_fma_f32 v47, v25, s68, v0
	v_fma_f32 v48, v8, s68, v0
	v_fma_f32 v49, v9, s68, v0
	v_fma_f32 v50, v26, s68, v0
	v_fma_f32 v51, v27, s68, v0
	v_fma_f32 v52, v10, s68, v0
	v_fma_f32 v53, v11, s68, v0
	v_fma_f32 v54, v28, s68, v0
	v_fma_f32 v55, v29, s68, v0
	v_fma_f32 v60, v12, s68, v0
	v_fma_f32 v61, v13, s68, v0
	v_fma_f32 v56, v30, s68, v0
	v_fma_f32 v57, v31, s68, v0
	v_fma_f32 v58, v14, s68, v0
	v_fma_f32 v59, v15, s68, v0
	v_fma_f32 v62, v32, s68, v0
	v_fma_f32 v63, v33, s68, v0
	v_fma_f32 v64, v16, s68, v0
	v_fma_f32 v65, v17, s68, v0
.LBB0_722:
	s_andn2_b64 vcc, exec, s[16:17]
	s_cbranch_vccnz .LBB0_724
	v_or_b32_e32 v0, s18, v159
	v_sub_u32_e32 v62, v226, v0
	v_med3_i32 v35, v62, 32, v202
	v_med3_i32 v34, v62, 0, v201
	v_lshl_add_u32 v35, v35, 2, s91
	v_lshl_add_u32 v34, v34, 2, s91
	v_add_u32_e32 v35, 0xffffff80, v35
	v_xad_u32 v0, v0, -1, v226
	ds_read_b32 v34, v34
	ds_read_b32 v36, v35
	v_med3_i32 v35, v0, 0, v201
	v_med3_i32 v0, v0, 32, v202
	v_lshl_add_u32 v0, v0, 2, s91
	v_add_u32_e32 v0, 0xffffff80, v0
	ds_read_b32 v37, v0
	v_lshl_add_u32 v35, v35, 2, s91
	ds_read_b32 v35, v35
	v_add_u32_e32 v0, -2, v62
	s_waitcnt lgkmcnt(1)
	v_fma_f32 v36, v2, s68, v36
	v_fma_f32 v37, v3, s68, v37
	v_med3_i32 v2, v0, 0, v201
	v_med3_i32 v0, v0, 32, v202
	v_lshl_add_u32 v0, v0, 2, s91
	v_lshl_add_u32 v2, v2, 2, s91
	v_add_u32_e32 v0, 0xffffff80, v0
	ds_read_b32 v2, v2
	s_waitcnt lgkmcnt(1)
	v_fma_f32 v34, v18, s68, v34
	v_fma_f32 v35, v19, s68, v35
	ds_read_b32 v18, v0
	v_add_u32_e32 v0, -3, v62
	v_med3_i32 v3, v0, 0, v201
	v_lshl_add_u32 v3, v3, 2, s91
	v_med3_i32 v0, v0, 32, v202
	ds_read_b32 v3, v3
	v_lshl_add_u32 v0, v0, 2, s91
	v_add_u32_e32 v0, 0xffffff80, v0
	ds_read_b32 v19, v0
	v_add_u32_e32 v0, -8, v62
	s_waitcnt lgkmcnt(1)
	v_fma_f32 v38, v20, s68, v2
	v_fma_f32 v39, v21, s68, v3
	v_med3_i32 v2, v0, 0, v201
	v_med3_i32 v0, v0, 32, v202
	v_lshl_add_u32 v0, v0, 2, s91
	v_lshl_add_u32 v2, v2, 2, s91
	v_add_u32_e32 v0, 0xffffff80, v0
	s_waitcnt lgkmcnt(0)
	v_fma_f32 v40, v4, s68, v18
	v_fma_f32 v41, v5, s68, v19
	ds_read_b32 v2, v2
	ds_read_b32 v4, v0
	v_add_u32_e32 v0, -9, v62
	v_med3_i32 v3, v0, 0, v201
	v_lshl_add_u32 v3, v3, 2, s91
	v_med3_i32 v0, v0, 32, v202
	ds_read_b32 v3, v3
	v_lshl_add_u32 v0, v0, 2, s91
	v_add_u32_e32 v0, 0xffffff80, v0
	ds_read_b32 v5, v0
	v_add_u32_e32 v0, -10, v62
	s_waitcnt lgkmcnt(1)
	v_fma_f32 v42, v22, s68, v2
	v_fma_f32 v43, v23, s68, v3
	v_med3_i32 v2, v0, 0, v201
	v_med3_i32 v0, v0, 32, v202
	v_lshl_add_u32 v0, v0, 2, s91
	v_lshl_add_u32 v2, v2, 2, s91
	v_add_u32_e32 v0, 0xffffff80, v0
	s_waitcnt lgkmcnt(0)
	v_fma_f32 v44, v6, s68, v4
	v_fma_f32 v45, v7, s68, v5
	ds_read_b32 v2, v2
	ds_read_b32 v4, v0
	v_add_u32_e32 v0, -11, v62
	v_med3_i32 v3, v0, 0, v201
	v_lshl_add_u32 v3, v3, 2, s91
	v_med3_i32 v0, v0, 32, v202
	ds_read_b32 v3, v3
	v_lshl_add_u32 v0, v0, 2, s91
	v_add_u32_e32 v0, 0xffffff80, v0
	ds_read_b32 v5, v0
	v_add_u32_e32 v0, -16, v62
	s_waitcnt lgkmcnt(1)
	v_fma_f32 v46, v24, s68, v2
	v_fma_f32 v47, v25, s68, v3
	v_med3_i32 v2, v0, 0, v201
	v_med3_i32 v0, v0, 32, v202
	v_lshl_add_u32 v0, v0, 2, s91
	v_lshl_add_u32 v2, v2, 2, s91
	v_add_u32_e32 v0, 0xffffff80, v0
	s_waitcnt lgkmcnt(0)
	v_fma_f32 v48, v8, s68, v4
	v_fma_f32 v49, v9, s68, v5
	ds_read_b32 v2, v2
	ds_read_b32 v4, v0
	v_subrev_u32_e32 v0, 17, v62
	v_med3_i32 v3, v0, 0, v201
	v_lshl_add_u32 v3, v3, 2, s91
	v_med3_i32 v0, v0, 32, v202
	ds_read_b32 v3, v3
	v_lshl_add_u32 v0, v0, 2, s91
	v_add_u32_e32 v0, 0xffffff80, v0
	ds_read_b32 v5, v0
	v_subrev_u32_e32 v0, 18, v62
	s_waitcnt lgkmcnt(1)
	v_fma_f32 v50, v26, s68, v2
	v_fma_f32 v51, v27, s68, v3
	v_med3_i32 v2, v0, 0, v201
	v_med3_i32 v0, v0, 32, v202
	v_lshl_add_u32 v0, v0, 2, s91
	v_lshl_add_u32 v2, v2, 2, s91
	v_add_u32_e32 v0, 0xffffff80, v0
	s_waitcnt lgkmcnt(0)
	v_fma_f32 v52, v10, s68, v4
	v_fma_f32 v53, v11, s68, v5
	ds_read_b32 v2, v2
	ds_read_b32 v4, v0
	v_subrev_u32_e32 v0, 19, v62
	v_med3_i32 v3, v0, 0, v201
	v_lshl_add_u32 v3, v3, 2, s91
	v_med3_i32 v0, v0, 32, v202
	ds_read_b32 v3, v3
	v_lshl_add_u32 v0, v0, 2, s91
	v_add_u32_e32 v0, 0xffffff80, v0
	ds_read_b32 v5, v0
	v_subrev_u32_e32 v0, 24, v62
	s_waitcnt lgkmcnt(1)
	v_fma_f32 v54, v28, s68, v2
	v_fma_f32 v55, v29, s68, v3
	v_med3_i32 v2, v0, 0, v201
	v_med3_i32 v0, v0, 32, v202
	v_lshl_add_u32 v0, v0, 2, s91
	v_lshl_add_u32 v2, v2, 2, s91
	v_add_u32_e32 v0, 0xffffff80, v0
	s_waitcnt lgkmcnt(0)
	v_fma_f32 v60, v12, s68, v4
	v_fma_f32 v61, v13, s68, v5
	ds_read_b32 v2, v2
	ds_read_b32 v4, v0
	v_subrev_u32_e32 v0, 25, v62
	v_med3_i32 v3, v0, 0, v201
	v_lshl_add_u32 v3, v3, 2, s91
	v_med3_i32 v0, v0, 32, v202
	ds_read_b32 v3, v3
	v_lshl_add_u32 v0, v0, 2, s91
	v_add_u32_e32 v0, 0xffffff80, v0
	ds_read_b32 v5, v0
	v_subrev_u32_e32 v0, 26, v62
	s_waitcnt lgkmcnt(1)
	v_fma_f32 v56, v30, s68, v2
	v_fma_f32 v57, v31, s68, v3
	v_med3_i32 v2, v0, 0, v201
	v_med3_i32 v0, v0, 32, v202
	v_lshl_add_u32 v0, v0, 2, s91
	v_lshl_add_u32 v2, v2, 2, s91
	v_add_u32_e32 v0, 0xffffff80, v0
	s_waitcnt lgkmcnt(0)
	v_fma_f32 v58, v14, s68, v4
	v_fma_f32 v59, v15, s68, v5
	ds_read_b32 v2, v2
	ds_read_b32 v4, v0
	v_subrev_u32_e32 v0, 27, v62
	v_med3_i32 v3, v0, 0, v201
	v_med3_i32 v0, v0, 32, v202
	v_lshl_add_u32 v0, v0, 2, s91
	v_lshl_add_u32 v3, v3, 2, s91
	v_add_u32_e32 v0, 0xffffff80, v0
	ds_read_b32 v3, v3
	ds_read_b32 v5, v0
	s_waitcnt lgkmcnt(1)
	v_fma_f32 v62, v32, s68, v2
	v_fma_f32 v63, v33, s68, v3
	s_waitcnt lgkmcnt(0)
	v_fma_f32 v64, v16, s68, v4
	v_fma_f32 v65, v17, s68, v5

.LBB0_728:
	v_add_f32_e32 v15, v15, v71
	v_add_f32_e32 v2, v14, v0
	v_add_f32_e32 v3, v15, v1
	v_add_f32_e32 v67, v67, v73
	v_add_f32_e32 v3, v2, v3
	v_add_f32_e32 v2, v2, v2
	v_mov_b32_e32 v73, v3
	v_add_f32_e32 v2, v66, v72
	v_add_f32_e32 v3, v67, v73
	v_add_f32_e32 v69, v69, v75
	v_add_f32_e32 v3, v2, v3
	v_add_f32_e32 v2, v2, v2
	v_mov_b32_e32 v75, v3
	v_add_f32_e32 v2, v68, v74
	v_add_f32_e32 v3, v69, v75
	v_add_f32_e32 v71, v77, v177
	v_add_f32_e32 v3, v2, v3
	v_add_f32_e32 v2, v2, v2
	v_mov_b32_e32 v77, v3
	v_add_f32_e32 v2, v70, v76
	v_add_f32_e32 v3, v71, v77
	v_add_f32_e32 v53, v79, v179
	v_add_f32_e32 v3, v2, v3
	v_add_f32_e32 v2, v2, v2
	v_mov_b32_e32 v79, v3
	v_add_f32_e32 v2, v52, v78
	v_add_f32_e32 v3, v53, v79
	v_add_f32_e32 v55, v151, v180
	v_add_f32_e32 v3, v2, v3
	v_add_f32_e32 v2, v2, v2
	v_mov_b32_e32 v61, v3
	v_add_f32_e32 v2, v54, v60
	v_add_f32_e32 v3, v55, v61
	v_add_f32_e32 v57, v181, v182
	v_add_f32_e32 v3, v2, v3
	v_add_f32_e32 v2, v2, v2
	v_mov_b32_e32 v177, v3
	v_add_f32_e32 v2, v56, v176
	v_add_f32_e32 v3, v57, v177
	v_add_f32_e32 v59, v59, v63
	v_add_f32_e32 v3, v2, v3
	v_add_f32_e32 v2, v2, v2
	v_mov_b32_e32 v63, v3
	v_add_f32_e32 v2, v58, v62
	v_add_f32_e32 v3, v59, v63
	s_nop 0
	v_add_f32_e32 v224, v2, v3
	v_fmac_f32_e32 v224, 0, v178
	s_branch .LBB0_738

.LBB0_738:
	s_cmp_gt_i32 s2, s8
	s_cselect_b64 s[16:17], -1, 0
	s_and_b64 s[16:17], s[16:17], s[42:43]
	s_andn2_b64 vcc, exec, s[16:17]
	s_cbranch_vccnz .LBB0_751
	s_lshl_b32 s2, s3, 6
	s_add_i32 s3, s2, s4
	s_ashr_i32 s18, s3, 6
	s_cmp_le_i32 s18, s40
	s_cselect_b64 s[16:17], -1, 0
	s_cmp_ge_i32 s18, s41
	s_cselect_b64 s[18:19], -1, 0
	s_and_b64 s[16:17], s[16:17], s[18:19]
	s_andn2_b64 vcc, exec, s[16:17]
	s_cbranch_vccnz .LBB0_751
	v_add_u32_e32 v0, v212, v210
	ds_read_b128 v[2:5], v0 offset:13824
	ds_read_b128 v[6:9], v0 offset:9216
	ds_read_b128 v[10:13], v0 offset:9248
	ds_read_b128 v[176:179], v0 offset:13856
	ds_read_b128 v[180:183], v0 offset:9280
	ds_read_b128 v[184:187], v0 offset:13888
	ds_read_b128 v[188:191], v0 offset:9312
	ds_read_b128 v[228:231], v0 offset:13920
	s_waitcnt lgkmcnt(6)
	v_mfma_f32_32x32x16_bf16 v[64:79], v[6:9], v[96:99], 0
	s_add_i32 s18, s3, 0xbf
	s_mov_b64 s[16:17], -1
	s_cmp_gt_i32 s18, s20
	v_mfma_f32_32x32x16_bf16 v[48:63], v[2:5], v[96:99], 0
	s_waitcnt lgkmcnt(5)
	v_mfma_f32_32x32x16_bf16 v[64:79], v[10:13], v[100:103], v[64:79]
	s_waitcnt lgkmcnt(4)
	v_mfma_f32_32x32x16_bf16 v[48:63], v[176:179], v[100:103], v[48:63]
	s_waitcnt lgkmcnt(3)
	v_mfma_f32_32x32x16_bf16 v[64:79], v[180:183], v[104:107], v[64:79]
	s_waitcnt lgkmcnt(2)
	v_mfma_f32_32x32x16_bf16 v[48:63], v[184:187], v[104:107], v[48:63]
	s_waitcnt lgkmcnt(1)
	v_mfma_f32_32x32x16_bf16 v[64:79], v[188:191], v[108:111], v[64:79]
	s_waitcnt lgkmcnt(0)
	v_mfma_f32_32x32x16_bf16 v[48:63], v[228:231], v[108:111], v[48:63]
	s_cbranch_scc1 .LBB0_742
	v_mov_b32_e32 v0, s29
	ds_read_b32 v0, v0
	s_mov_b64 s[16:17], 0
	s_waitcnt lgkmcnt(0)
	s_nop 4
	v_fma_f32 v2, v64, s68, v0
	v_fma_f32 v3, v65, s68, v0
	s_nop 0
	v_fma_f32 v4, v48, s68, v0
	v_fma_f32 v5, v49, s68, v0
	v_fma_f32 v6, v66, s68, v0
	v_fma_f32 v7, v67, s68, v0
	v_fma_f32 v8, v50, s68, v0
	v_fma_f32 v9, v51, s68, v0
	v_fma_f32 v10, v68, s68, v0
	v_fma_f32 v11, v69, s68, v0
	v_fma_f32 v12, v52, s68, v0
	v_fma_f32 v13, v53, s68, v0
	v_fma_f32 v14, v70, s68, v0
	v_fma_f32 v15, v71, s68, v0
	v_fma_f32 v176, v54, s68, v0
	v_fma_f32 v177, v55, s68, v0
	v_fma_f32 v178, v72, s68, v0
	v_fma_f32 v179, v73, s68, v0
	v_fma_f32 v180, v56, s68, v0
	v_fma_f32 v181, v57, s68, v0
	v_fma_f32 v182, v74, s68, v0
	v_fma_f32 v183, v75, s68, v0
	v_fma_f32 v184, v58, s68, v0
	v_fma_f32 v185, v59, s68, v0
	v_fma_f32 v186, v76, s68, v0
	v_fma_f32 v187, v77, s68, v0
	v_fma_f32 v188, v60, s68, v0
	v_fma_f32 v189, v61, s68, v0
	v_fma_f32 v190, v78, s68, v0
	v_fma_f32 v191, v79, s68, v0
	v_fma_f32 v192, v62, s68, v0
	v_fma_f32 v193, v63, s68, v0
.LBB0_742:
	s_andn2_b64 vcc, exec, s[16:17]
	s_cbranch_vccnz .LBB0_744
	v_or_b32_e32 v0, s3, v159
	v_sub_u32_e32 v151, v226, v0
	v_med3_i32 v3, v151, 32, v202
	v_med3_i32 v2, v151, 0, v201
	v_lshl_add_u32 v3, v3, 2, s91
	v_lshl_add_u32 v2, v2, 2, s91
	v_add_u32_e32 v3, 0xffffff80, v3
	v_xad_u32 v0, v0, -1, v226
	ds_read_b32 v2, v2
	ds_read_b32 v4, v3
	v_med3_i32 v3, v0, 0, v201
	v_med3_i32 v0, v0, 32, v202
	v_lshl_add_u32 v0, v0, 2, s91
	v_add_u32_e32 v0, 0xffffff80, v0
	ds_read_b32 v5, v0
	v_add_u32_e32 v0, -2, v151
	v_med3_i32 v6, v0, 0, v201
	v_med3_i32 v0, v0, 32, v202
	v_lshl_add_u32 v0, v0, 2, s91
	v_lshl_add_u32 v3, v3, 2, s91
	v_add_u32_e32 v0, 0xffffff80, v0
	ds_read_b32 v3, v3
	ds_read_b32 v8, v0
	v_add_u32_e32 v0, -3, v151
	v_med3_i32 v7, v0, 0, v201
	v_med3_i32 v0, v0, 32, v202
	v_lshl_add_u32 v0, v0, 2, s91
	v_lshl_add_u32 v6, v6, 2, s91
	v_add_u32_e32 v0, 0xffffff80, v0
	ds_read_b32 v6, v6
	ds_read_b32 v9, v0
	v_add_u32_e32 v0, -8, v151
	v_med3_i32 v10, v0, 0, v201
	v_med3_i32 v0, v0, 32, v202
	v_lshl_add_u32 v0, v0, 2, s91
	v_lshl_add_u32 v7, v7, 2, s91
	v_add_u32_e32 v0, 0xffffff80, v0
	ds_read_b32 v7, v7
	ds_read_b32 v12, v0
	v_add_u32_e32 v0, -9, v151
	v_med3_i32 v11, v0, 0, v201
	v_med3_i32 v0, v0, 32, v202
	v_lshl_add_u32 v0, v0, 2, s91
	v_lshl_add_u32 v10, v10, 2, s91
	v_add_u32_e32 v0, 0xffffff80, v0
	ds_read_b32 v10, v10
	ds_read_b32 v13, v0
	v_add_u32_e32 v0, -10, v151
	v_med3_i32 v14, v0, 0, v201
	v_med3_i32 v0, v0, 32, v202
	v_lshl_add_u32 v0, v0, 2, s91
	v_lshl_add_u32 v11, v11, 2, s91
	v_add_u32_e32 v0, 0xffffff80, v0
	s_waitcnt lgkmcnt(8)
	v_fma_f32 v4, v48, s68, v4
	v_fma_f32 v5, v49, s68, v5
	ds_read_b32 v11, v11
	ds_read_b32 v48, v0
	v_add_u32_e32 v0, -11, v151
	v_med3_i32 v15, v0, 0, v201
	v_med3_i32 v0, v0, 32, v202
	v_lshl_add_u32 v0, v0, 2, s91
	v_lshl_add_u32 v14, v14, 2, s91
	v_add_u32_e32 v0, 0xffffff80, v0
	ds_read_b32 v14, v14
	ds_read_b32 v49, v0
	v_add_u32_e32 v0, -16, v151
	v_lshl_add_u32 v15, v15, 2, s91
	s_waitcnt lgkmcnt(8)
	v_fma_f32 v8, v50, s68, v8
	v_fma_f32 v9, v51, s68, v9
	ds_read_b32 v15, v15
	s_waitcnt lgkmcnt(1)
	v_fma_f32 v176, v54, s68, v48
	v_fma_f32 v177, v55, s68, v49
	v_med3_i32 v48, v0, 0, v201
	v_med3_i32 v0, v0, 32, v202
	v_lshl_add_u32 v0, v0, 2, s91
	v_add_u32_e32 v0, 0xffffff80, v0
	ds_read_b32 v50, v0
	v_subrev_u32_e32 v0, 17, v151
	v_med3_i32 v49, v0, 0, v201
	v_lshl_add_u32 v48, v48, 2, s91
	v_lshl_add_u32 v49, v49, 2, s91
	ds_read_b32 v48, v48
	ds_read_b32 v49, v49
	v_med3_i32 v0, v0, 32, v202
	v_lshl_add_u32 v0, v0, 2, s91
	v_add_u32_e32 v0, 0xffffff80, v0
	ds_read_b32 v51, v0
	v_subrev_u32_e32 v0, 18, v151
	s_waitcnt lgkmcnt(1)
	v_fma_f32 v178, v72, s68, v48
	v_fma_f32 v179, v73, s68, v49
	v_med3_i32 v48, v0, 0, v201
	v_med3_i32 v0, v0, 32, v202
	v_lshl_add_u32 v0, v0, 2, s91
	v_lshl_add_u32 v48, v48, 2, s91
	v_add_u32_e32 v0, 0xffffff80, v0
	s_waitcnt lgkmcnt(0)
	v_fma_f32 v180, v56, s68, v50
	v_fma_f32 v181, v57, s68, v51
	ds_read_b32 v48, v48
	ds_read_b32 v50, v0
	v_subrev_u32_e32 v0, 19, v151
	v_med3_i32 v49, v0, 0, v201
	v_lshl_add_u32 v49, v49, 2, s91
	v_med3_i32 v0, v0, 32, v202
	ds_read_b32 v49, v49
	v_lshl_add_u32 v0, v0, 2, s91
	v_add_u32_e32 v0, 0xffffff80, v0
	ds_read_b32 v51, v0
	v_subrev_u32_e32 v0, 24, v151
	s_waitcnt lgkmcnt(1)
	v_fma_f32 v182, v74, s68, v48
	v_fma_f32 v183, v75, s68, v49
	v_med3_i32 v48, v0, 0, v201
	v_med3_i32 v0, v0, 32, v202
	v_lshl_add_u32 v0, v0, 2, s91
	v_lshl_add_u32 v48, v48, 2, s91
	v_add_u32_e32 v0, 0xffffff80, v0
	s_waitcnt lgkmcnt(0)
	v_fma_f32 v184, v58, s68, v50
	v_fma_f32 v185, v59, s68, v51
	ds_read_b32 v48, v48
	ds_read_b32 v50, v0
	v_subrev_u32_e32 v0, 25, v151
	v_med3_i32 v49, v0, 0, v201
	v_lshl_add_u32 v49, v49, 2, s91
	v_med3_i32 v0, v0, 32, v202
	ds_read_b32 v49, v49
	v_lshl_add_u32 v0, v0, 2, s91
	v_add_u32_e32 v0, 0xffffff80, v0
	ds_read_b32 v51, v0
	v_subrev_u32_e32 v0, 26, v151
	s_waitcnt lgkmcnt(1)
	v_fma_f32 v186, v76, s68, v48
	v_fma_f32 v187, v77, s68, v49
	v_med3_i32 v48, v0, 0, v201
	v_med3_i32 v0, v0, 32, v202
	v_lshl_add_u32 v0, v0, 2, s91
	v_lshl_add_u32 v48, v48, 2, s91
	v_add_u32_e32 v0, 0xffffff80, v0
	s_waitcnt lgkmcnt(0)
	v_fma_f32 v188, v60, s68, v50
	v_fma_f32 v189, v61, s68, v51
	ds_read_b32 v48, v48
	ds_read_b32 v50, v0
	v_subrev_u32_e32 v0, 27, v151
	v_med3_i32 v49, v0, 0, v201
	v_med3_i32 v0, v0, 32, v202
	v_lshl_add_u32 v0, v0, 2, s91
	v_lshl_add_u32 v49, v49, 2, s91
	v_add_u32_e32 v0, 0xffffff80, v0
	ds_read_b32 v49, v49
	ds_read_b32 v51, v0
	v_fma_f32 v2, v64, s68, v2
	v_fma_f32 v3, v65, s68, v3
	v_fma_f32 v6, v66, s68, v6
	v_fma_f32 v7, v67, s68, v7
	v_fma_f32 v10, v68, s68, v10
	v_fma_f32 v11, v69, s68, v11
	v_fma_f32 v12, v52, s68, v12
	v_fma_f32 v13, v53, s68, v13
	v_fma_f32 v14, v70, s68, v14
	v_fma_f32 v15, v71, s68, v15
	s_waitcnt lgkmcnt(1)
	v_fma_f32 v190, v78, s68, v48
	v_fma_f32 v191, v79, s68, v49
	s_waitcnt lgkmcnt(0)
	v_fma_f32 v192, v62, s68, v50
	v_fma_f32 v193, v63, s68, v51

.LBB0_746:
	v_max_f32_e32 v0, v5, v5
	s_nop 2
	v_max_f32_e32 v48, v3, v3
	v_max_f32_e32 v0, v48, v0
	v_max_f32_e32 v48, v8, v8
	v_max_f32_e32 v49, v6, v6
	v_max_f32_e32 v48, v49, v48
	v_max_f32_e32 v49, v9, v9
	v_max_f32_e32 v50, v7, v7
	v_max3_f32 v0, v2, v4, v0
	v_max_f32_e32 v49, v50, v49
	v_max3_f32 v0, v0, v48, v49
	v_max_f32_e32 v48, v12, v12
	v_max_f32_e32 v49, v10, v10
	v_max_f32_e32 v48, v49, v48
	v_max_f32_e32 v49, v13, v13
	v_max_f32_e32 v50, v11, v11
	v_max_f32_e32 v49, v50, v49
	v_max3_f32 v0, v0, v48, v49
	v_max_f32_e32 v48, v176, v176
	v_max_f32_e32 v49, v14, v14
	v_max_f32_e32 v48, v49, v48
	v_max_f32_e32 v49, v177, v177
	v_max_f32_e32 v50, v15, v15
	v_max_f32_e32 v49, v50, v49
	v_max3_f32 v0, v0, v48, v49
	v_max_f32_e32 v48, v180, v180
	v_max_f32_e32 v49, v178, v178
	v_max_f32_e32 v48, v49, v48
	v_max_f32_e32 v49, v181, v181
	v_max_f32_e32 v50, v179, v179
	v_max_f32_e32 v49, v50, v49
	v_max3_f32 v0, v0, v48, v49
	v_max_f32_e32 v48, v184, v184
	v_max_f32_e32 v49, v182, v182
	v_max_f32_e32 v48, v49, v48
	v_max_f32_e32 v49, v185, v185
	v_max_f32_e32 v50, v183, v183
	v_max_f32_e32 v49, v50, v49
	v_max3_f32 v0, v0, v48, v49
	v_max_f32_e32 v48, v188, v188
	v_max_f32_e32 v49, v186, v186
	v_max_f32_e32 v48, v49, v48
	v_max_f32_e32 v49, v189, v189
	v_max_f32_e32 v50, v187, v187
	v_max_f32_e32 v49, v50, v49
	v_max3_f32 v0, v0, v48, v49
	v_max_f32_e32 v48, v192, v192
	v_max_f32_e32 v49, v190, v190
	v_max_f32_e32 v48, v49, v48
	v_max_f32_e32 v49, v193, v193
	v_max_f32_e32 v50, v191, v191
	v_max_f32_e32 v49, v50, v49
	v_max3_f32 v0, v0, v48, v49
	v_and_b32_e32 v49, 64, v199
	v_xor_b32_e32 v48, 32, v199
	v_add_u32_e32 v49, 64, v49
	v_cmp_lt_i32_e32 vcc, v48, v49
	s_nop 1
	v_cndmask_b32_e32 v48, v199, v48, vcc
	v_lshlrev_b32_e32 v48, 2, v48
	ds_bpermute_b32 v48, v48, v0
	s_waitcnt lgkmcnt(0)
	v_max3_f32 v52, v225, v0, v48
	v_sub_f32_e32 v0, v225, v52
	v_exp_f32_e32 v0, v0
	s_nop 0
	v_cmp_eq_f32_e32 vcc, 1.0, v0
	s_cmp_eq_u64 vcc, exec
	s_cbranch_scc1 .LBB0_748
	v_mul_f32_e32 v46, v46, v0
	v_mul_f32_e32 v47, v47, v0
	v_mul_f32_e32 v44, v44, v0
	v_mul_f32_e32 v45, v45, v0
	v_mul_f32_e32 v42, v42, v0
	v_mul_f32_e32 v43, v43, v0
	v_mul_f32_e32 v40, v40, v0
	v_mul_f32_e32 v41, v41, v0
	v_mul_f32_e32 v38, v38, v0
	v_mul_f32_e32 v39, v39, v0
	v_mul_f32_e32 v36, v36, v0
	v_mul_f32_e32 v37, v37, v0
	v_mul_f32_e32 v34, v34, v0
	v_mul_f32_e32 v35, v35, v0
	v_mul_f32_e32 v32, v32, v0
	v_mul_f32_e32 v33, v33, v0
	v_mul_f32_e32 v30, v30, v0
	v_mul_f32_e32 v31, v31, v0
	v_mul_f32_e32 v28, v28, v0
	v_mul_f32_e32 v29, v29, v0
	v_mul_f32_e32 v26, v26, v0
	v_mul_f32_e32 v27, v27, v0
	v_mul_f32_e32 v24, v24, v0
	v_mul_f32_e32 v25, v25, v0
	v_mul_f32_e32 v22, v22, v0
	v_mul_f32_e32 v23, v23, v0
	v_mul_f32_e32 v20, v20, v0
	v_mul_f32_e32 v21, v21, v0
	v_mul_f32_e32 v18, v18, v0
	v_mul_f32_e32 v19, v19, v0
	v_mul_f32_e32 v16, v16, v0
	v_mul_f32_e32 v17, v17, v0

.LBB0_778:
	s_add_i32 s16, s4, s2
	s_add_i32 s17, s16, 0xffffff40
	s_lshr_b32 s17, s17, 6
	s_cmp_le_i32 s17, s40
	s_cselect_b64 s[18:19], -1, 0
	s_cmp_ge_i32 s17, s41
	s_cselect_b64 s[26:27], -1, 0
	s_and_b64 s[18:19], s[18:19], s[26:27]
	s_andn2_b64 vcc, exec, s[18:19]
	s_cbranch_vccnz .LBB0_790
	v_add3_u32 v0, s24, v209, v210
	ds_read_b128 v[2:5], v0 offset:4608
	ds_read_b128 v[6:9], v0
	ds_read_b128 v[10:13], v0 offset:32
	ds_read_b128 v[176:179], v0 offset:4640
	ds_read_b128 v[180:183], v0 offset:64
	ds_read_b128 v[184:187], v0 offset:4672
	ds_read_b128 v[188:191], v0 offset:96
	ds_read_b128 v[228:231], v0 offset:4704
	s_waitcnt lgkmcnt(6)
	v_mfma_f32_32x32x16_bf16 v[64:79], v[6:9], v[96:99], 0
	s_add_i32 s18, s16, -1
	s_mov_b64 s[16:17], -1
	s_cmp_gt_i32 s18, s20
	v_mfma_f32_32x32x16_bf16 v[48:63], v[2:5], v[96:99], 0
	s_waitcnt lgkmcnt(5)
	v_mfma_f32_32x32x16_bf16 v[64:79], v[10:13], v[100:103], v[64:79]
	s_waitcnt lgkmcnt(4)
	v_mfma_f32_32x32x16_bf16 v[48:63], v[176:179], v[100:103], v[48:63]
	s_waitcnt lgkmcnt(3)
	v_mfma_f32_32x32x16_bf16 v[64:79], v[180:183], v[104:107], v[64:79]
	s_waitcnt lgkmcnt(2)
	v_mfma_f32_32x32x16_bf16 v[48:63], v[184:187], v[104:107], v[48:63]
	s_waitcnt lgkmcnt(1)
	v_mfma_f32_32x32x16_bf16 v[64:79], v[188:191], v[108:111], v[64:79]
	s_waitcnt lgkmcnt(0)
	v_mfma_f32_32x32x16_bf16 v[48:63], v[228:231], v[108:111], v[48:63]
	s_cbranch_scc1 .LBB0_781
	v_mov_b32_e32 v0, s29
	ds_read_b32 v0, v0
	s_mov_b64 s[16:17], 0
	s_waitcnt lgkmcnt(0)
	s_nop 4
	v_fma_f32 v2, v64, s68, v0
	v_fma_f32 v3, v65, s68, v0
	s_nop 0
	v_fma_f32 v4, v48, s68, v0
	v_fma_f32 v5, v49, s68, v0
	v_fma_f32 v6, v66, s68, v0
	v_fma_f32 v7, v67, s68, v0
	v_fma_f32 v8, v50, s68, v0
	v_fma_f32 v9, v51, s68, v0
	v_fma_f32 v10, v68, s68, v0
	v_fma_f32 v11, v69, s68, v0
	v_fma_f32 v12, v52, s68, v0
	v_fma_f32 v13, v53, s68, v0
	v_fma_f32 v14, v70, s68, v0
	v_fma_f32 v15, v71, s68, v0
	v_fma_f32 v176, v54, s68, v0
	v_fma_f32 v177, v55, s68, v0
	v_fma_f32 v178, v72, s68, v0
	v_fma_f32 v179, v73, s68, v0
	v_fma_f32 v180, v56, s68, v0
	v_fma_f32 v181, v57, s68, v0
	v_fma_f32 v182, v74, s68, v0
	v_fma_f32 v183, v75, s68, v0
	v_fma_f32 v184, v58, s68, v0
	v_fma_f32 v185, v59, s68, v0
	v_fma_f32 v186, v76, s68, v0
	v_fma_f32 v187, v77, s68, v0
	v_fma_f32 v188, v60, s68, v0
	v_fma_f32 v189, v61, s68, v0
	v_fma_f32 v190, v78, s68, v0
	v_fma_f32 v191, v79, s68, v0
	v_fma_f32 v192, v62, s68, v0
	v_fma_f32 v193, v63, s68, v0
.LBB0_781:
	s_andn2_b64 vcc, exec, s[16:17]
	s_cbranch_vccnz .LBB0_783
	v_subrev_u32_e32 v0, 64, v226
	v_med3_i32 v2, v0, 0, v201
	v_med3_i32 v0, v0, 32, v202
	v_lshl_add_u32 v0, v0, 2, s91
	v_lshl_add_u32 v2, v2, 2, s91
	v_add_u32_e32 v0, 0xffffff80, v0
	ds_read_b32 v2, v2
	ds_read_b32 v4, v0
	v_add_u32_e32 v0, 0xffffffbf, v226
	v_med3_i32 v3, v0, 0, v201
	v_med3_i32 v0, v0, 32, v202
	v_lshl_add_u32 v0, v0, 2, s91
	v_lshl_add_u32 v3, v3, 2, s91
	v_add_u32_e32 v0, 0xffffff80, v0
	ds_read_b32 v3, v3
	ds_read_b32 v5, v0
	v_add_u32_e32 v0, 0xffffffbe, v226
	v_med3_i32 v6, v0, 0, v201
	v_med3_i32 v0, v0, 32, v202
	v_lshl_add_u32 v0, v0, 2, s91
	v_lshl_add_u32 v6, v6, 2, s91
	v_add_u32_e32 v0, 0xffffff80, v0
	ds_read_b32 v6, v6
	ds_read_b32 v8, v0
	v_add_u32_e32 v0, 0xffffffbd, v226
	v_med3_i32 v7, v0, 0, v201
	v_med3_i32 v0, v0, 32, v202
	v_lshl_add_u32 v0, v0, 2, s91
	v_lshl_add_u32 v7, v7, 2, s91
	v_add_u32_e32 v0, 0xffffff80, v0
	ds_read_b32 v7, v7
	ds_read_b32 v9, v0
	v_add_u32_e32 v0, 0xffffffb8, v226
	v_med3_i32 v10, v0, 0, v201
	v_med3_i32 v0, v0, 32, v202
	v_lshl_add_u32 v0, v0, 2, s91
	v_lshl_add_u32 v10, v10, 2, s91
	v_add_u32_e32 v0, 0xffffff80, v0
	ds_read_b32 v10, v10
	ds_read_b32 v12, v0
	v_add_u32_e32 v0, 0xffffffb7, v226
	v_med3_i32 v11, v0, 0, v201
	v_med3_i32 v0, v0, 32, v202
	v_lshl_add_u32 v0, v0, 2, s91
	v_lshl_add_u32 v11, v11, 2, s91
	v_add_u32_e32 v0, 0xffffff80, v0
	ds_read_b32 v11, v11
	ds_read_b32 v13, v0
	v_add_u32_e32 v0, 0xffffffb6, v226
	v_med3_i32 v14, v0, 0, v201
	v_med3_i32 v0, v0, 32, v202
	v_lshl_add_u32 v0, v0, 2, s91
	v_lshl_add_u32 v14, v14, 2, s91
	v_add_u32_e32 v0, 0xffffff80, v0
	s_waitcnt lgkmcnt(8)
	v_fma_f32 v4, v48, s68, v4
	v_fma_f32 v5, v49, s68, v5
	ds_read_b32 v14, v14
	ds_read_b32 v48, v0
	v_add_u32_e32 v0, 0xffffffb5, v226
	v_med3_i32 v15, v0, 0, v201
	v_med3_i32 v0, v0, 32, v202
	v_lshl_add_u32 v0, v0, 2, s91
	v_lshl_add_u32 v15, v15, 2, s91
	v_add_u32_e32 v0, 0xffffff80, v0
	ds_read_b32 v15, v15
	ds_read_b32 v49, v0
	v_add_u32_e32 v0, 0xffffffb0, v226
	s_waitcnt lgkmcnt(8)
	v_fma_f32 v8, v50, s68, v8
	v_fma_f32 v9, v51, s68, v9
	v_fma_f32 v2, v64, s68, v2
	v_fma_f32 v3, v65, s68, v3
	v_fma_f32 v6, v66, s68, v6
	v_fma_f32 v7, v67, s68, v7
	s_waitcnt lgkmcnt(0)
	v_fma_f32 v176, v54, s68, v48
	v_fma_f32 v177, v55, s68, v49
	v_med3_i32 v48, v0, 0, v201
	v_med3_i32 v0, v0, 32, v202
	v_lshl_add_u32 v0, v0, 2, s91
	v_lshl_add_u32 v48, v48, 2, s91
	v_add_u32_e32 v0, 0xffffff80, v0
	ds_read_b32 v48, v48
	ds_read_b32 v50, v0
	v_add_u32_e32 v0, 0xffffffaf, v226
	v_med3_i32 v49, v0, 0, v201
	v_lshl_add_u32 v49, v49, 2, s91
	v_med3_i32 v0, v0, 32, v202
	ds_read_b32 v49, v49
	v_lshl_add_u32 v0, v0, 2, s91
	v_add_u32_e32 v0, 0xffffff80, v0
	ds_read_b32 v51, v0
	v_add_u32_e32 v0, 0xffffffae, v226
	s_waitcnt lgkmcnt(1)
	v_fma_f32 v178, v72, s68, v48
	v_fma_f32 v179, v73, s68, v49
	v_med3_i32 v48, v0, 0, v201
	v_med3_i32 v0, v0, 32, v202
	v_lshl_add_u32 v0, v0, 2, s91
	v_lshl_add_u32 v48, v48, 2, s91
	v_add_u32_e32 v0, 0xffffff80, v0
	s_waitcnt lgkmcnt(0)
	v_fma_f32 v180, v56, s68, v50
	v_fma_f32 v181, v57, s68, v51
	ds_read_b32 v48, v48
	ds_read_b32 v50, v0
	v_add_u32_e32 v0, 0xffffffad, v226
	v_med3_i32 v49, v0, 0, v201
	v_lshl_add_u32 v49, v49, 2, s91
	v_med3_i32 v0, v0, 32, v202
	ds_read_b32 v49, v49
	v_lshl_add_u32 v0, v0, 2, s91
	v_add_u32_e32 v0, 0xffffff80, v0
	ds_read_b32 v51, v0
	v_add_u32_e32 v0, 0xffffffa8, v226
	s_waitcnt lgkmcnt(1)
	v_fma_f32 v182, v74, s68, v48
	v_fma_f32 v183, v75, s68, v49
	v_med3_i32 v48, v0, 0, v201
	v_med3_i32 v0, v0, 32, v202
	v_lshl_add_u32 v0, v0, 2, s91
	v_lshl_add_u32 v48, v48, 2, s91
	v_add_u32_e32 v0, 0xffffff80, v0
	s_waitcnt lgkmcnt(0)
	v_fma_f32 v184, v58, s68, v50
	v_fma_f32 v185, v59, s68, v51
	ds_read_b32 v48, v48
	ds_read_b32 v50, v0
	v_add_u32_e32 v0, 0xffffffa7, v226
	v_med3_i32 v49, v0, 0, v201
	v_lshl_add_u32 v49, v49, 2, s91
	v_med3_i32 v0, v0, 32, v202
	ds_read_b32 v49, v49
	v_lshl_add_u32 v0, v0, 2, s91
	v_add_u32_e32 v0, 0xffffff80, v0
	ds_read_b32 v51, v0
	v_add_u32_e32 v0, 0xffffffa6, v226
	s_waitcnt lgkmcnt(1)
	v_fma_f32 v186, v76, s68, v48
	v_fma_f32 v187, v77, s68, v49
	v_med3_i32 v48, v0, 0, v201
	v_med3_i32 v0, v0, 32, v202
	v_lshl_add_u32 v0, v0, 2, s91
	v_lshl_add_u32 v48, v48, 2, s91
	v_add_u32_e32 v0, 0xffffff80, v0
	s_waitcnt lgkmcnt(0)
	v_fma_f32 v188, v60, s68, v50
	v_fma_f32 v189, v61, s68, v51
	ds_read_b32 v48, v48
	ds_read_b32 v50, v0
	v_add_u32_e32 v0, 0xffffffa5, v226
	v_med3_i32 v49, v0, 0, v201
	v_med3_i32 v0, v0, 32, v202
	v_lshl_add_u32 v0, v0, 2, s91
	v_lshl_add_u32 v49, v49, 2, s91
	v_add_u32_e32 v0, 0xffffff80, v0
	ds_read_b32 v49, v49
	ds_read_b32 v51, v0
	v_fma_f32 v10, v68, s68, v10
	v_fma_f32 v11, v69, s68, v11
	v_fma_f32 v12, v52, s68, v12
	v_fma_f32 v13, v53, s68, v13
	v_fma_f32 v14, v70, s68, v14
	v_fma_f32 v15, v71, s68, v15
	s_waitcnt lgkmcnt(1)
	v_fma_f32 v190, v78, s68, v48
	v_fma_f32 v191, v79, s68, v49
	s_waitcnt lgkmcnt(0)
	v_fma_f32 v192, v62, s68, v50
	v_fma_f32 v193, v63, s68, v51

.LBB0_790:
	s_cmp_gt_i32 s48, s8
	s_cselect_b64 s[16:17], -1, 0
	s_and_b64 s[16:17], s[16:17], s[42:43]
	s_andn2_b64 vcc, exec, s[16:17]
	s_cbranch_vccnz .LBB0_803
	s_add_i32 s16, s4, s2
	s_add_i32 s17, s16, 0xffffff00
	s_ashr_i32 s17, s17, 6
	s_cmp_le_i32 s17, s40
	s_cselect_b64 s[18:19], -1, 0
	s_cmp_ge_i32 s17, s41
	s_cselect_b64 s[24:25], -1, 0
	s_and_b64 s[18:19], s[18:19], s[24:25]
	s_andn2_b64 vcc, exec, s[18:19]
	s_cbranch_vccnz .LBB0_803
	v_add3_u32 v0, s22, v209, v210
	ds_read_b128 v[2:5], v0 offset:4608
	ds_read_b128 v[6:9], v0
	ds_read_b128 v[10:13], v0 offset:32
	ds_read_b128 v[176:179], v0 offset:4640
	ds_read_b128 v[180:183], v0 offset:64
	ds_read_b128 v[184:187], v0 offset:4672
	ds_read_b128 v[188:191], v0 offset:96
	ds_read_b128 v[228:231], v0 offset:4704
	s_waitcnt lgkmcnt(6)
	v_mfma_f32_32x32x16_bf16 v[64:79], v[6:9], v[96:99], 0
	s_add_i32 s18, s16, 0xffffffbf
	s_mov_b64 s[16:17], -1
	s_cmp_gt_i32 s18, s20
	v_mfma_f32_32x32x16_bf16 v[48:63], v[2:5], v[96:99], 0
	s_waitcnt lgkmcnt(5)
	v_mfma_f32_32x32x16_bf16 v[64:79], v[10:13], v[100:103], v[64:79]
	s_waitcnt lgkmcnt(4)
	v_mfma_f32_32x32x16_bf16 v[48:63], v[176:179], v[100:103], v[48:63]
	s_waitcnt lgkmcnt(3)
	v_mfma_f32_32x32x16_bf16 v[64:79], v[180:183], v[104:107], v[64:79]
	s_waitcnt lgkmcnt(2)
	v_mfma_f32_32x32x16_bf16 v[48:63], v[184:187], v[104:107], v[48:63]
	s_waitcnt lgkmcnt(1)
	v_mfma_f32_32x32x16_bf16 v[64:79], v[188:191], v[108:111], v[64:79]
	s_waitcnt lgkmcnt(0)
	v_mfma_f32_32x32x16_bf16 v[48:63], v[228:231], v[108:111], v[48:63]
	s_cbranch_scc1 .LBB0_794
	v_mov_b32_e32 v0, s29
	ds_read_b32 v0, v0
	s_mov_b64 s[16:17], 0
	s_waitcnt lgkmcnt(0)
	s_nop 4
	v_fma_f32 v2, v64, s68, v0
	v_fma_f32 v3, v65, s68, v0
	s_nop 0
	v_fma_f32 v4, v48, s68, v0
	v_fma_f32 v5, v49, s68, v0
	v_fma_f32 v6, v66, s68, v0
	v_fma_f32 v7, v67, s68, v0
	v_fma_f32 v8, v50, s68, v0
	v_fma_f32 v9, v51, s68, v0
	v_fma_f32 v10, v68, s68, v0
	v_fma_f32 v11, v69, s68, v0
	v_fma_f32 v12, v52, s68, v0
	v_fma_f32 v13, v53, s68, v0
	v_fma_f32 v14, v70, s68, v0
	v_fma_f32 v15, v71, s68, v0
	v_fma_f32 v176, v54, s68, v0
	v_fma_f32 v177, v55, s68, v0
	v_fma_f32 v178, v72, s68, v0
	v_fma_f32 v179, v73, s68, v0
	v_fma_f32 v180, v56, s68, v0
	v_fma_f32 v181, v57, s68, v0
	v_fma_f32 v182, v74, s68, v0
	v_fma_f32 v183, v75, s68, v0
	v_fma_f32 v184, v58, s68, v0
	v_fma_f32 v185, v59, s68, v0
	v_fma_f32 v186, v76, s68, v0
	v_fma_f32 v187, v77, s68, v0
	v_fma_f32 v188, v60, s68, v0
	v_fma_f32 v189, v61, s68, v0
	v_fma_f32 v190, v78, s68, v0
	v_fma_f32 v191, v79, s68, v0
	v_fma_f32 v192, v62, s68, v0
	v_fma_f32 v193, v63, s68, v0
.LBB0_794:
	s_andn2_b64 vcc, exec, s[16:17]
	s_cbranch_vccnz .LBB0_796
	v_med3_i32 v0, v226, 0, v201
	v_med3_i32 v3, v226, 32, v202
	v_lshl_add_u32 v0, v0, 2, s91
	ds_read_b32 v2, v0
	v_lshl_add_u32 v0, v3, 2, s91
	v_add_u32_e32 v0, 0xffffff80, v0
	ds_read_b32 v4, v0
	v_add_u32_e32 v0, -1, v226
	v_med3_i32 v3, v0, 0, v201
	v_med3_i32 v0, v0, 32, v202
	v_lshl_add_u32 v0, v0, 2, s91
	v_lshl_add_u32 v3, v3, 2, s91
	v_add_u32_e32 v0, 0xffffff80, v0
	ds_read_b32 v3, v3
	ds_read_b32 v5, v0
	v_add_u32_e32 v0, -2, v226
	v_med3_i32 v6, v0, 0, v201
	v_med3_i32 v0, v0, 32, v202
	v_lshl_add_u32 v0, v0, 2, s91
	v_lshl_add_u32 v6, v6, 2, s91
	v_add_u32_e32 v0, 0xffffff80, v0
	ds_read_b32 v6, v6
	ds_read_b32 v8, v0
	v_add_u32_e32 v0, -3, v226
	v_med3_i32 v7, v0, 0, v201
	v_med3_i32 v0, v0, 32, v202
	v_lshl_add_u32 v0, v0, 2, s91
	v_lshl_add_u32 v7, v7, 2, s91
	v_add_u32_e32 v0, 0xffffff80, v0
	ds_read_b32 v7, v7
	ds_read_b32 v9, v0
	v_add_u32_e32 v0, -8, v226
	v_med3_i32 v10, v0, 0, v201
	v_med3_i32 v0, v0, 32, v202
	v_lshl_add_u32 v0, v0, 2, s91
	v_lshl_add_u32 v10, v10, 2, s91
	v_add_u32_e32 v0, 0xffffff80, v0
	ds_read_b32 v10, v10
	ds_read_b32 v12, v0
	v_add_u32_e32 v0, -9, v226
	v_med3_i32 v11, v0, 0, v201
	v_med3_i32 v0, v0, 32, v202
	v_lshl_add_u32 v0, v0, 2, s91
	v_lshl_add_u32 v11, v11, 2, s91
	v_add_u32_e32 v0, 0xffffff80, v0
	ds_read_b32 v11, v11
	ds_read_b32 v13, v0
	v_add_u32_e32 v0, -10, v226
	v_med3_i32 v14, v0, 0, v201
	v_med3_i32 v0, v0, 32, v202
	v_lshl_add_u32 v0, v0, 2, s91
	v_lshl_add_u32 v14, v14, 2, s91
	v_add_u32_e32 v0, 0xffffff80, v0
	s_waitcnt lgkmcnt(8)
	v_fma_f32 v4, v48, s68, v4
	v_fma_f32 v5, v49, s68, v5
	ds_read_b32 v14, v14
	ds_read_b32 v48, v0
	v_add_u32_e32 v0, -11, v226
	v_med3_i32 v15, v0, 0, v201
	v_med3_i32 v0, v0, 32, v202
	v_lshl_add_u32 v0, v0, 2, s91
	v_lshl_add_u32 v15, v15, 2, s91
	v_add_u32_e32 v0, 0xffffff80, v0
	ds_read_b32 v15, v15
	ds_read_b32 v49, v0
	v_add_u32_e32 v0, -16, v226
	s_waitcnt lgkmcnt(8)
	v_fma_f32 v8, v50, s68, v8
	v_fma_f32 v9, v51, s68, v9
	v_fma_f32 v2, v64, s68, v2
	v_fma_f32 v3, v65, s68, v3
	v_fma_f32 v6, v66, s68, v6
	v_fma_f32 v7, v67, s68, v7
	s_waitcnt lgkmcnt(0)
	v_fma_f32 v176, v54, s68, v48
	v_fma_f32 v177, v55, s68, v49
	v_med3_i32 v48, v0, 0, v201
	v_med3_i32 v0, v0, 32, v202
	v_lshl_add_u32 v0, v0, 2, s91
	v_lshl_add_u32 v48, v48, 2, s91
	v_add_u32_e32 v0, 0xffffff80, v0
	ds_read_b32 v48, v48
	ds_read_b32 v50, v0
	v_subrev_u32_e32 v0, 17, v226
	v_med3_i32 v49, v0, 0, v201
	v_lshl_add_u32 v49, v49, 2, s91
	v_med3_i32 v0, v0, 32, v202
	ds_read_b32 v49, v49
	v_lshl_add_u32 v0, v0, 2, s91
	v_add_u32_e32 v0, 0xffffff80, v0
	ds_read_b32 v51, v0
	v_subrev_u32_e32 v0, 18, v226
	s_waitcnt lgkmcnt(1)
	v_fma_f32 v178, v72, s68, v48
	v_fma_f32 v179, v73, s68, v49
	v_med3_i32 v48, v0, 0, v201
	v_med3_i32 v0, v0, 32, v202
	v_lshl_add_u32 v0, v0, 2, s91
	v_lshl_add_u32 v48, v48, 2, s91
	v_add_u32_e32 v0, 0xffffff80, v0
	s_waitcnt lgkmcnt(0)
	v_fma_f32 v180, v56, s68, v50
	v_fma_f32 v181, v57, s68, v51
	ds_read_b32 v48, v48
	ds_read_b32 v50, v0
	v_subrev_u32_e32 v0, 19, v226
	v_med3_i32 v49, v0, 0, v201
	v_lshl_add_u32 v49, v49, 2, s91
	v_med3_i32 v0, v0, 32, v202
	ds_read_b32 v49, v49
	v_lshl_add_u32 v0, v0, 2, s91
	v_add_u32_e32 v0, 0xffffff80, v0
	ds_read_b32 v51, v0
	v_subrev_u32_e32 v0, 24, v226
	s_waitcnt lgkmcnt(1)
	v_fma_f32 v182, v74, s68, v48
	v_fma_f32 v183, v75, s68, v49
	v_med3_i32 v48, v0, 0, v201
	v_med3_i32 v0, v0, 32, v202
	v_lshl_add_u32 v0, v0, 2, s91
	v_lshl_add_u32 v48, v48, 2, s91
	v_add_u32_e32 v0, 0xffffff80, v0
	s_waitcnt lgkmcnt(0)
	v_fma_f32 v184, v58, s68, v50
	v_fma_f32 v185, v59, s68, v51
	ds_read_b32 v48, v48
	ds_read_b32 v50, v0
	v_subrev_u32_e32 v0, 25, v226
	v_med3_i32 v49, v0, 0, v201
	v_lshl_add_u32 v49, v49, 2, s91
	v_med3_i32 v0, v0, 32, v202
	ds_read_b32 v49, v49
	v_lshl_add_u32 v0, v0, 2, s91
	v_add_u32_e32 v0, 0xffffff80, v0
	ds_read_b32 v51, v0
	v_subrev_u32_e32 v0, 26, v226
	s_waitcnt lgkmcnt(1)
	v_fma_f32 v186, v76, s68, v48
	v_fma_f32 v187, v77, s68, v49
	v_med3_i32 v48, v0, 0, v201
	v_med3_i32 v0, v0, 32, v202
	v_lshl_add_u32 v0, v0, 2, s91
	v_lshl_add_u32 v48, v48, 2, s91
	v_add_u32_e32 v0, 0xffffff80, v0
	s_waitcnt lgkmcnt(0)
	v_fma_f32 v188, v60, s68, v50
	v_fma_f32 v189, v61, s68, v51
	ds_read_b32 v48, v48
	ds_read_b32 v50, v0
	v_subrev_u32_e32 v0, 27, v226
	v_med3_i32 v49, v0, 0, v201
	v_med3_i32 v0, v0, 32, v202
	v_lshl_add_u32 v0, v0, 2, s91
	v_lshl_add_u32 v49, v49, 2, s91
	v_add_u32_e32 v0, 0xffffff80, v0
	ds_read_b32 v49, v49
	ds_read_b32 v51, v0
	v_fma_f32 v10, v68, s68, v10
	v_fma_f32 v11, v69, s68, v11
	v_fma_f32 v12, v52, s68, v12
	v_fma_f32 v13, v53, s68, v13
	v_fma_f32 v14, v70, s68, v14
	v_fma_f32 v15, v71, s68, v15
	s_waitcnt lgkmcnt(1)
	v_fma_f32 v190, v78, s68, v48
	v_fma_f32 v191, v79, s68, v49
	s_waitcnt lgkmcnt(0)
	v_fma_f32 v192, v62, s68, v50
	v_fma_f32 v193, v63, s68, v51
